# LRU r-gate: cl folded into the reciprocal (fma(e,1/cl,1/cl) then rcp), one multiply fewer per element in both passes
# speedup vs baseline: 1.0153x; 1.0030x over previous
; template <int dir>
; __device__ __forceinline__ void lru_pass(LAS unsigned char* lds, const Params& P, int b, int h, int q, bool dry) {
;     const int tid = opaque_tid(), lane = tid & 63, wid = __builtin_amdgcn_readfirstlane(tid >> 6), g = lane >> 5, nl = lane & 31;
;     const int chl = q * 32 + nl, ch = h * 128 + chl;
;     LAS unsigned char* XC = lds;
;     LAS float* AGG = (LAS float*)(lds + 256 * XC_PITCH);
;     LAS unsigned char* WB = lds + 256 * XC_PITCH + 2048;
;     LAS float* CWL = (LAS float*)(lds + 256 * XC_PITCH + 2048 + 64 * XC_PITCH);
;     LAS unsigned char* TIN = lds + LRU_IO_OFF;
;     LAS unsigned char* TOUT = lds + LRU_IO_OFF + 256 * (dir == 0 ? IO_NP : IO_WP);
;     bf16_t* Z = (bf16_t*)(P.ws + WS_Z); const bf16_t* ZC = (const bf16_t*)(P.ws + WS_ZC); unsigned* HFW = (unsigned*)(P.ws + WS_HF);
;     const bf16_t* LruW = (const bf16_t*)(P.ws + WS_LRUW);
;     const int cgp = tid & 15, tr = tid >> 4;
;     const int s_i = 16 * ((nl >> 2) & 1) + ((nl >> 3) << 2) + (nl & 3);
;     const bf16_t* Zg = Z + ZSLAB(8 + h, (size_t)b * SEQ) + q * 32;
;     unsigned* Hg = HFW + (size_t)b * SEQ * DM + h * 128 + q * 32;
;     {
; #pragma unroll
;         for (int i = 0; i < 2; ++i) { const int idx = tid + i * NTHREADS, gate = idx >> 9, n = (idx >> 4) & 31, kc = idx & 15;
;             *(LAS u32x4*)(WB + (gate * 32 + n) * XC_PITCH + kc * 16) = *(const u32x4*)(LruW + ((size_t)((dir * 2 + gate) * 8 + h) * 128 + q * 32 + n) * 128 + kc * 8); }
;         const float br = -LOG2E * P.lru_ba[(dir * 8 + h) * 128 + chl], bi = -LOG2E * P.lru_bx[(dir * 8 + h) * 128 + chl];
;         const float lam = P.lru_lambda[dir * 1024 + ch];
;         const float cl = -8.0f * LOG2E * log1pf(__expf(-lam));
;         float carry = 0.f;
;         LruTile cur = lru_tile(Z, ZC, b, h, dir, 0);
;         u32x4 rows[11];
;         constexpr int NIN = dir == 0 ? 2 : 4;
;         u32x4 inr[NIN];
; __device__ __forceinline__ void lru_strip(LAS unsigned char* lds, const Params& P, int strip, bool dry) {
;     const int tid = opaque_tid();
;     const int b = strip >> 5, h = (strip >> 2) & 7, q = strip & 3;
;     LAS float* CWL = (LAS float*)(lds + 256 * XC_PITCH + 2048 + 64 * XC_PITCH);
;     for (int i = tid; i < 640; i += NTHREADS) { const int k = i >> 7, c = i & 127; CWL[i] = k < 4 ? P.conv_w[k * 1024 + h * 128 + c] : P.conv_b[h * 128 + c]; }
.LBB0_278:
	s_ashr_i32 s25, s2, 3
	v_mov_b32_e32 v128, v167
	s_bfe_u32 s26, s25, 0x30002
	s_lshl_b32 s27, s26, 7
	v_and_b32_e32 v204, 0x7f, v128
	v_or_b32_e32 v204, s27, v204
	v_lshrrev_b32_e32 v205, 7, v128
	v_lshl_or_b32 v205, v205, 10, v204
	v_lshlrev_b32_e32 v205, 2, v205
	v_lshlrev_b32_e32 v204, 2, v204
	global_load_dword v205, v205, s[52:53]
	global_load_dword v204, v204, s[54:55]
	v_readlane_b32 s0, v255, 19
	s_nop 3
	v_lshl_add_u32 v206, v128, 2, s0
	v_mov_b32_e32 v12, v167
	s_lshl_b32 s0, s25, 5
	s_and_b32 s28, s0, 0x60
	v_and_b32_e32 v15, 31, v12
	v_or_b32_e32 v17, s28, v15
	v_add_u32_e32 v14, 0x200, v12
	v_or_b32_e32 v11, s27, v17
	v_ashrrev_i32_e32 v8, 9, v12
	v_ashrrev_i32_e32 v10, 9, v14
	v_lshlrev_b32_e32 v16, 2, v11
	v_and_b32_e32 v13, 15, v12
	v_lshl_or_b32 v2, v8, 3, s26
	v_lshl_or_b32 v6, v10, 3, s26
	global_load_dword v18, v16, s[64:65]
	v_bfe_u32 v9, v12, 4, 5
	v_lshlrev_b32_e32 v64, 4, v13
	v_ashrrev_i32_e32 v3, 31, v2
	v_ashrrev_i32_e32 v7, 31, v6
	v_or_b32_e32 v4, s28, v9
	v_lshl_add_u64 v[0:1], s[38:39], 0, v[64:65]
	v_lshlrev_b64 v[2:3], 15, v[2:3]
	v_lshlrev_b64 v[6:7], 15, v[6:7]
	v_lshlrev_b32_e32 v4, 8, v4
	v_mov_b32_e32 v5, v65
	v_lshl_add_u64 v[2:3], v[0:1], 0, v[2:3]
	v_lshl_add_u64 v[0:1], v[0:1], 0, v[6:7]
	v_lshl_add_u64 v[2:3], v[2:3], 0, v[4:5]
	v_lshl_add_u64 v[4:5], v[0:1], 0, v[4:5]
	global_load_dwordx4 v[0:3], v[2:3], off
	s_nop 0
	global_load_dwordx4 v[4:7], v[4:5], off
	v_lshlrev_b32_e32 v11, 2, v12
	v_lshl_or_b32 v21, v8, 5, v9
	v_add_u32_e32 v8, s88, v64
	v_lshl_or_b32 v9, v10, 5, v9
	v_and_b32_e32 v22, 16, v11
	v_mad_u64_u32 v[10:11], s[4:5], v21, s89, v[8:9]
	v_mad_u64_u32 v[8:9], s[4:5], v9, s89, v[8:9]
	global_load_dword v9, v16, s[58:59]
	global_load_dword v11, v16, s[62:63]
	s_lshl_b32 s0, s2, 5
	s_and_b32 s0, s0, 0xe0
	s_or_b32 s1, s0, s25
	s_ashr_i32 s78, s1, 5
	s_ashr_i32 s79, s78, 31
	s_lshl_b32 s20, s26, 22
	s_lshl_b64 s[18:19], s[78:79], 19
	s_lshl_b64 s[44:45], s[78:79], 23
	v_readlane_b32 s1, v255, 18
	s_add_u32 s1, s1, s44
	s_addc_u32 s4, s33, s45
	s_lshl_b32 s5, s27, 2
	s_add_u32 s1, s1, s5
	s_addc_u32 s4, s4, 0
	s_add_u32 s5, s68, s18
	s_addc_u32 s6, s69, s19
	s_lshl_b32 s7, s27, 1
	s_add_u32 s48, s5, s7
	s_addc_u32 s49, s6, 0
	s_add_u32 s50, s48, 0x1000
	s_addc_u32 s51, s49, 0
	s_add_u32 s56, s48, 0x1800
	s_addc_u32 s57, s49, 0
	s_add_u32 s60, s48, 0x2000
	s_addc_u32 s61, s49, 0
	s_add_u32 s66, s48, 0x2800
	s_addc_u32 s67, s49, 0
	s_add_u32 s70, s48, 0x3000
	s_addc_u32 s71, s49, 0
	v_ashrrev_i32_e32 v36, 4, v12
	v_lshlrev_b32_e32 v37, 3, v13
	s_add_u32 s72, s48, 0x3800
	s_addc_u32 s73, s49, 0
	s_add_u32 s74, s48, 0x4000
	s_addc_u32 s75, s49, 0
	s_add_u32 s76, s48, 0x4800
	s_addc_u32 s77, s49, 0
	v_readfirstlane_b32 s0, v12
	s_ashr_i32 s6, s0, 6
	s_lshl_b32 s5, s28, 2
	s_add_u32 s8, s1, s5
	v_bfe_u32 v19, v12, 5, 1
	v_lshrrev_b32_e32 v20, 1, v12
	v_and_b32_e32 v33, 3, v12
	s_addc_u32 s9, s4, 0
	v_lshl_or_b32 v110, v36, 13, v37
	v_mov_b32_e32 v111, v65
	v_lshlrev_b64 v[110:111], 1, v[110:111]
	v_lshl_add_u64 v[108:109], s[48:49], 0, v[110:111]
	global_load_dwordx4 v[68:71], v[108:109], off offset:-2048
	global_load_dwordx4 v[72:75], v[108:109], off
	global_load_dwordx4 v[76:79], v[108:109], off offset:2048
	v_lshl_add_u64 v[108:109], s[50:51], 0, v[110:111]
	global_load_dwordx4 v[80:83], v[108:109], off
	v_lshl_add_u64 v[108:109], s[56:57], 0, v[110:111]
	global_load_dwordx4 v[84:87], v[108:109], off
	v_lshl_add_u64 v[108:109], s[60:61], 0, v[110:111]
	global_load_dwordx4 v[88:91], v[108:109], off
	v_lshl_add_u64 v[108:109], s[66:67], 0, v[110:111]
	global_load_dwordx4 v[92:95], v[108:109], off
	v_lshl_add_u64 v[108:109], s[70:71], 0, v[110:111]
	global_load_dwordx4 v[96:99], v[108:109], off
	v_lshl_add_u64 v[108:109], s[72:73], 0, v[110:111]
	global_load_dwordx4 v[100:103], v[108:109], off
	v_lshl_add_u64 v[108:109], s[74:75], 0, v[110:111]
	global_load_dwordx4 v[104:107], v[108:109], off
	v_lshl_add_u64 v[108:109], s[76:77], 0, v[110:111]
	global_load_dwordx4 v[108:111], v[108:109], off
	s_waitcnt vmcnt(14)
	ds_write_b128 v10, v[0:3]
	s_waitcnt vmcnt(13)
	ds_write_b128 v8, v[4:7]
	ds_write_b32 v206, v205
	v_cmp_gt_u32_e32 vcc, 0x80, v128
	s_and_saveexec_b64 s[14:15], vcc
	ds_write_b32 v206, v204 offset:2048
	s_or_b64 exec, exec, s[14:15]
	v_mul_f32_e32 v16, 0xbfb8aa3b, v18
	v_exp_f32_e32 v16, v16
	s_lshl_b32 s1, s6, 5
	s_and_b32 s0, s0, 0x3fffffc0
	v_add_u32_e32 v39, 0, v64
	v_add_f32_e32 v2, 1.0, v16
	v_add_f32_e32 v3, -1.0, v2
	v_frexp_mant_f32_e32 v4, v2
	v_cvt_f64_f32_e32 v[0:1], v2
	v_sub_f32_e32 v5, v3, v2
	v_frexp_exp_i32_f64_e32 v0, v[0:1]
	v_cmp_gt_f32_e32 vcc, s80, v4
	v_sub_f32_e32 v3, v16, v3
	v_add_f32_e32 v1, 1.0, v5
	v_subbrev_co_u32_e32 v0, vcc, 0, v0, vcc
	v_add_f32_e32 v1, v3, v1
	v_sub_u32_e32 v3, 0, v0
	v_ldexp_f32 v2, v2, v3
	v_ldexp_f32 v1, v1, v3
	v_add_f32_e32 v3, -1.0, v2
	v_add_f32_e32 v4, 1.0, v2
	v_add_f32_e32 v5, 1.0, v3
	v_add_f32_e32 v6, -1.0, v4
	v_sub_f32_e32 v5, v2, v5
	v_sub_f32_e32 v2, v2, v6
	v_add_f32_e32 v5, v1, v5
	v_add_f32_e32 v1, v1, v2
	v_add_f32_e32 v6, v4, v1
	v_rcp_f32_e32 v7, v6
	v_add_f32_e32 v2, v3, v5
	v_sub_f32_e32 v4, v6, v4
	v_sub_f32_e32 v3, v2, v3
	v_sub_f32_e32 v1, v1, v4
	v_mul_f32_e32 v4, v2, v7
	v_sub_f32_e32 v3, v5, v3
	v_mul_f32_e32 v5, v6, v4
	v_fma_f32 v8, v4, v6, -v5
	v_fmac_f32_e32 v8, v4, v1
	v_add_f32_e32 v10, v5, v8
	v_sub_f32_e32 v18, v2, v10
	v_sub_f32_e32 v2, v2, v18
	v_sub_f32_e32 v5, v10, v5
	v_sub_f32_e32 v2, v2, v10
	v_sub_f32_e32 v5, v5, v8
	v_add_f32_e32 v2, v3, v2
	v_add_f32_e32 v2, v5, v2
	v_add_f32_e32 v3, v18, v2
	v_mul_f32_e32 v5, v7, v3
	v_mul_f32_e32 v10, v6, v5
	v_fma_f32 v6, v5, v6, -v10
; template <int dir>
; __device__ __forceinline__ void lru_pass(LAS unsigned char* lds, const Params& P, int b, int h, int q, bool dry) {
;     ...
;         const float br = -LOG2E * P.lru_ba[(dir * 8 + h) * 128 + chl], bi = -LOG2E * P.lru_bx[(dir * 8 + h) * 128 + chl];
;         const float lam = P.lru_lambda[dir * 1024 + ch];
;         const float cl = -8.0f * LOG2E * log1pf(__expf(-lam));
	v_fmac_f32_e32 v6, v5, v1
	v_add_f32_e32 v1, v10, v6
	v_sub_f32_e32 v8, v18, v3
	v_sub_f32_e32 v18, v3, v1
	v_sub_f32_e32 v3, v3, v18
	v_add_f32_e32 v2, v2, v8
	v_sub_f32_e32 v10, v1, v10
	v_sub_f32_e32 v1, v3, v1
	v_sub_f32_e32 v6, v10, v6
	v_add_f32_e32 v1, v2, v1
	v_cvt_f32_i32_e32 v0, v0
	v_add_f32_e32 v8, v4, v5
	v_add_f32_e32 v1, v6, v1
	v_add_f32_e32 v1, v18, v1
	v_sub_f32_e32 v2, v8, v4
	v_mul_f32_e32 v1, v7, v1
	v_sub_f32_e32 v2, v5, v2
	v_add_f32_e32 v1, v2, v1
	v_mul_f32_e32 v5, 0x3f317218, v0
	v_add_f32_e32 v2, v8, v1
	v_fma_f32 v6, v0, s81, -v5
	v_fmac_f32_e32 v6, 0xb102e308, v0
	v_sub_f32_e32 v0, v2, v8
	v_mul_f32_e32 v3, v2, v2
	v_sub_f32_e32 v0, v1, v0
	v_add_f32_e32 v1, v5, v6
	v_fmamk_f32 v4, v3, 0x3e9b6dac, v200
	v_sub_f32_e32 v5, v1, v5
	v_fmaak_f32 v4, v3, v4, 0x3f2aaada
	v_sub_f32_e32 v5, v6, v5
	v_ldexp_f32 v6, v2, 1
	v_mul_f32_e32 v2, v2, v3
	v_mul_f32_e32 v2, v2, v4
	v_add_f32_e32 v3, v6, v2
	v_sub_f32_e32 v4, v3, v6
	v_ldexp_f32 v0, v0, 1
	v_sub_f32_e32 v2, v2, v4
	v_add_f32_e32 v0, v0, v2
	v_add_f32_e32 v2, v3, v0
	v_sub_f32_e32 v3, v2, v3
	v_sub_f32_e32 v0, v0, v3
	v_add_f32_e32 v3, v1, v2
	v_sub_f32_e32 v4, v3, v1
	v_sub_f32_e32 v6, v3, v4
	v_sub_f32_e32 v1, v1, v6
	v_sub_f32_e32 v2, v2, v4
	v_add_f32_e32 v1, v2, v1
	v_add_f32_e32 v2, v5, v0
	v_sub_f32_e32 v4, v2, v5
	v_add_f32_e32 v1, v2, v1
	v_sub_f32_e32 v6, v2, v4
	v_add_f32_e32 v2, v3, v1
	v_sub_f32_e32 v5, v5, v6
	v_sub_f32_e32 v0, v0, v4
	v_sub_f32_e32 v3, v2, v3
	v_add_f32_e32 v0, v0, v5
	v_sub_f32_e32 v1, v1, v3
	v_add_f32_e32 v0, v0, v1
	v_add_f32_e32 v0, v2, v0
	v_cmp_neq_f32_e32 vcc, s91, v16
	v_mov_b32_e32 v1, v65
	v_lshlrev_b32_e32 v41, 4, v19
	v_cndmask_b32_e32 v0, v201, v0, vcc
	v_cmp_ngt_f32_e32 vcc, -1.0, v16
	s_cmp_eq_u32 s6, 7
	v_or_b32_e32 v35, s1, v41
	v_cndmask_b32_e32 v0, v202, v0, vcc
	v_cmp_neq_f32_e32 vcc, -1.0, v16
	v_ashrrev_i32_e32 v32, 2, v12
	v_ashrrev_i32_e32 v34, 2, v14
	v_cndmask_b32_e32 v0, v203, v0, vcc
	v_cmp_lt_f32_e64 vcc, |v16|, s92
	v_lshlrev_b32_e32 v53, 4, v33
	v_mul_lo_u32 v48, v32, s87
	v_cndmask_b32_e32 v6, v0, v16, vcc
	v_lshlrev_b32_e32 v1, 2, v15
	v_lshlrev_b32_e32 v2, 4, v12
	v_add_u32_e32 v140, s94, v1
	v_and_b32_e32 v3, 48, v2
	v_and_b32_e32 v64, 0x70, v2
	v_and_or_b32 v2, v20, 12, v33
	v_or3_b32 v2, v2, v22, s1
	v_lshl_add_u32 v147, s0, 2, v140
	s_cselect_b64 s[0:1], -1, 0
	s_cmp_eq_u32 s6, 6
	s_cselect_b64 s[16:17], -1, 0
	s_cmp_eq_u32 s6, 5
	s_cselect_b64 s[4:5], -1, 0
	s_cmp_eq_u32 s6, 4
	v_lshl_add_u64 v[130:131], s[8:9], 0, v[64:65]
	s_cselect_b64 s[8:9], -1, 0
	s_cmp_eq_u32 s6, 3
	s_cselect_b64 s[10:11], -1, 0
	s_cmp_eq_u32 s6, 2
	s_cselect_b64 s[12:13], -1, 0
	s_cmp_eq_u32 s6, 1
	s_cselect_b64 s[14:15], -1, 0
	s_add_u32 s46, s20, s18
	s_addc_u32 s47, 0, s19
	s_lshl_b32 s6, s2, 3
	v_ashrrev_i32_e32 v33, 31, v32
	v_mul_lo_u32 v50, v35, s89
	v_mul_lo_u32 v51, v35, s87
	v_mul_lo_u32 v52, v35, s30
	v_ashrrev_i32_e32 v35, 31, v34
	s_bfe_u32 s29, s2, 0x20003
	s_and_b32 s6, s6, 0xc0
	v_lshlrev_b64 v[32:33], 8, v[32:33]
	v_mul_lo_u32 v2, v2, s89
	v_add_u32_e32 v46, s96, v1
	v_mul_lo_u32 v49, v34, s87
	v_add_u32_e32 v1, 0x400, v12
	v_lshlrev_b64 v[34:35], 8, v[34:35]
	v_lshl_add_u64 v[32:33], s[46:47], 0, v[32:33]
	s_add_u32 s18, s82, s46
	v_lshlrev_b32_e32 v38, 5, v13
	v_add_u32_e32 v129, s96, v64
	v_add_u32_e32 v42, 0, v2
	v_mov_b32_e32 v2, s88
	v_ashrrev_i32_e32 v143, 3, v1
	v_add_u32_e32 v1, 0x600, v12
	v_lshl_add_u64 v[34:35], s[46:47], 0, v[34:35]
	v_or3_b32 v32, v32, s6, v53
	v_lshl_or_b32 v64, v36, 10, v37
	s_addc_u32 s19, s83, s47
	v_mov_b32_e32 v66, v65
	v_mov_b32_e32 v67, v65
	s_waitcnt vmcnt(12)
	v_mul_f32_e32 v0, 0xbfb8aa3b, v9
	s_waitcnt vmcnt(11)
; template <int dir>
; __device__ __forceinline__ void lru_pass(LAS unsigned char* lds, const Params& P, int b, int h, int q, bool dry) {
;     ...
;         const float br = -LOG2E * P.lru_ba[(dir * 8 + h) * 128 + chl], bi = -LOG2E * P.lru_bx[(dir * 8 + h) * 128 + chl];
;         const float lam = P.lru_lambda[dir * 1024 + ch];
;         const float cl = -8.0f * LOG2E * log1pf(__expf(-lam));
;         float carry = 0.f;
;         LruTile cur = lru_tile(Z, ZC, b, h, dir, 0);
;         u32x4 rows[11];
;         constexpr int NIN = dir == 0 ? 2 : 4;
;         u32x4 inr[NIN];
;         lru_load_rows(rows, cur, tr, cgp);
; #pragma unroll
;         for (int i = 0; i < NIN; ++i) inr[i] = (u32x4){0u, 0u, 0u, 0u};
;         int t0_prev = 0;
;     ...
;             f32x16 zr, zi;
; #pragma unroll
;             for (int v = 0; v < 16; ++v) { zr[v] = br; zi[v] = bi; }
;             const int sbase = 32 * wid + 16 * g;
	v_mul_f32_e32 v16, 0xbfb8aa3b, v11
	v_add_u32_e32 v40, s95, v3
	v_mad_u32_u24 v43, v15, s89, v2
	v_lshl_add_u32 v44, v17, 1, 0
	v_lshl_add_u32 v45, v15, 1, s95
	v_mul_lo_u32 v47, v36, s93
	v_ashrrev_i32_e32 v148, 3, v12
	v_ashrrev_i32_e32 v145, 3, v14
	v_ashrrev_i32_e32 v141, 3, v1
	v_or3_b32 v34, v34, s6, v53
	v_lshl_add_u64 v[134:135], s[40:41], 0, v[32:33]
	v_lshl_add_u64 v[136:137], v[64:65], 1, s[18:19]
	v_mov_b32_e32 v64, v65
	v_add_u32_e32 v32, 0, v38
	v_mov_b64_e32 v[114:115], v[66:67]
	v_mov_b64_e32 v[118:119], v[66:67]
	s_mov_b32 s90, 0
	v_mul_f32_e32 v138, 0xc138aa3b, v6
	v_rcp_f32_e32 v138, v138
	s_nop 0
	v_lshl_add_u32 v139, v36, 3, -1
	v_cmp_eq_u32_e32 vcc, 0, v19
	v_mul_lo_u32 v149, v148, s30
	v_mul_lo_u32 v146, v145, s30
	v_mul_lo_u32 v144, v143, s30
	v_mul_lo_u32 v142, v141, s30
	v_mov_b32_e32 v1, v0
	v_mov_b32_e32 v2, v0
	v_mov_b32_e32 v3, v0
	v_mov_b32_e32 v4, v0
	v_mov_b32_e32 v5, v0
	v_mov_b32_e32 v6, v0
	v_mov_b32_e32 v7, v0
	v_mov_b32_e32 v8, v0
	v_mov_b32_e32 v9, v0
	v_mov_b32_e32 v10, v0
	v_mov_b32_e32 v11, v0
	v_mov_b32_e32 v12, v0
	v_mov_b32_e32 v13, v0
	v_mov_b32_e32 v14, v0
	v_mov_b32_e32 v15, v0
	v_mov_b32_e32 v17, v16
	v_mov_b32_e32 v18, v16
	v_mov_b32_e32 v19, v16
	v_mov_b32_e32 v20, v16
	v_mov_b32_e32 v21, v16
	v_mov_b32_e32 v22, v16
	v_mov_b32_e32 v23, v16
	v_mov_b32_e32 v24, v16
	v_mov_b32_e32 v25, v16
	v_mov_b32_e32 v26, v16
	v_mov_b32_e32 v27, v16
	v_mov_b32_e32 v28, v16
	v_mov_b32_e32 v29, v16
	v_mov_b32_e32 v30, v16
	v_mov_b32_e32 v31, v16
	v_lshl_add_u64 v[132:133], s[40:41], 0, v[34:35]
	s_movk_i32 s92, 0x100
	v_mov_b32_e32 v165, 0
	s_mov_b64 s[80:81], 0
	v_add_u32_e32 v150, 0x15c00, v32
	v_add_u32_e32 v151, v39, v47
	v_add_u32_e32 v158, v40, v48
	v_add_u32_e32 v159, v40, v49
	v_add_u32_e32 v160, v42, v41
	v_add_u32_e32 v161, v43, v41
	v_add_u32_e32 v162, v44, v50
	v_add_u32_e32 v163, v45, v51
	v_add_u32_e32 v164, v46, v52
	v_mov_b64_e32 v[112:113], v[64:65]
	v_mov_b64_e32 v[116:117], v[64:65]
	s_mov_b32 s91, 0
	s_mov_b32 s93, 0
	s_mov_b32 s97, 0
	v_lshrrev_b32_e32 v254, 8, v167
	v_mul_u32_u24_e32 v252, 0x1400, v254
	v_add_u32_e32 v158, v158, v252
	v_add_u32_e32 v159, v159, v252
	v_add_u32_e32 v159, 0xffffec00, v159
	v_lshlrev_b32_e32 v252, 14, v254
	v_mov_b32_e32 v253, 0
	v_lshl_add_u64 v[134:135], v[252:253], 0, v[134:135]
	v_lshl_add_u64 v[132:133], v[252:253], 0, v[132:133]
	s_mov_b32 s18, 0xffffc000
	s_mov_b32 s19, -1
	v_lshl_add_u64 v[132:133], v[132:133], 0, s[18:19]
	v_mul_u32_u24_e32 v252, 0x3600, v254
	v_add_u32_e32 v149, v149, v252
	v_add_u32_e32 v146, v146, v252
	v_add_u32_e32 v144, v144, v252
	v_add_u32_e32 v142, v142, v252
	v_add_u32_e32 v146, 0xffffee00, v146
	v_add_u32_e32 v144, 0xffffdc00, v144
	v_add_u32_e32 v142, 0xffffca00, v142
	v_mul_u32_u24_e32 v252, 0x60, v254
	v_add_u32_e32 v148, v148, v252
	v_add_u32_e32 v145, v145, v252
	v_add_u32_e32 v143, v143, v252
	v_add_u32_e32 v141, v141, v252
	v_add_u32_e32 v145, 0xffffffe0, v145
	v_add_u32_e32 v143, 0xffffffc0, v143
	v_add_u32_e32 v141, 0xffffffa0, v141
	v_lshrrev_b32_e32 v253, 6, v167
	s_nop 1
	v_readfirstlane_b32 s18, v253
	s_lshr_b32 s101, s18, 2
	s_or_b32 s19, s18, 4
	s_cmp_eq_u32 s19, 7
	s_cselect_b64 s[0:1], -1, 0
	s_cmp_eq_u32 s19, 6
	s_cselect_b64 s[16:17], -1, 0
	s_cmp_eq_u32 s19, 5
	s_cselect_b64 s[4:5], -1, 0
	s_cmp_eq_u32 s19, 4
	s_cselect_b64 s[8:9], -1, 0
	s_mov_b64 s[10:11], 0
	s_mov_b64 s[12:13], 0
	s_mov_b64 s[14:15], 0
	s_mov_b32 s98, 0
	s_cmp_eq_u32 s101, 0
	s_cselect_b32 s99, 0x14400, 0
	s_cselect_b32 s100, 0, 0x400
	v_add_u32_e32 v253, 0x14000, v147
	v_mov_b32_e32 v254, 1.0
	v_mov_b32_e32 v252, 0
	ds_write2_b32 v253, v254, v252 offset1:32
	s_waitcnt lgkmcnt(0)
	s_barrier
	s_cmp_eq_u32 s101, 0
	s_cbranch_scc1 .Lpp_f_nox
	s_barrier

; #define LAS __attribute__((address_space(3)))
; template <int dir>
; __device__ __forceinline__ void lru_pass(LAS unsigned char* lds, const Params& P, int b, int h, int q, bool dry) {
;     ...
;             { const int sl = 32 * wid + s_i; const int tlA = dir == 0 ? sl : 255 - sl;
;               const LAS unsigned char* ap = XC + tlA * XC_PITCH + 16 * g;
;               const LAS unsigned char* wrp = WB + nl * XC_PITCH + 16 * g; const LAS unsigned char* wip = wrp + 32 * XC_PITCH;
; #pragma unroll
;               for (int ks = 0; ks < 8; ++ks) { const bf16x8 A = *(const LAS bf16x8*)(ap + 32 * ks);
;                   const bf16x8 Br = *(const LAS bf16x8*)(wrp + 32 * ks), Bi = *(const LAS bf16x8*)(wip + 32 * ks);
;                   zr = __builtin_amdgcn_mfma_f32_32x32x16_bf16(A, Br, zr, 0, 0, 0); zi = __builtin_amdgcn_mfma_f32_32x32x16_bf16(A, Bi, zi, 0, 0, 0); } }
;             unsigned xcb[16], pk[16];
; #pragma unroll
;             for (int v = 0; v < 16; ++v) { const int s = sbase + v; const int tl = dir == 0 ? s : 255 - s; xcb[v] = *(const LAS bf16_t*)(XC + tl * XC_PITCH + chl * 2);
;                 if (dir == 0) pk[v] = *(const LAS bf16_t*)(TIN + tl * IO_NP + nl * 2); else pk[v] = *(const LAS unsigned*)(TIN + tl * IO_WP + nl * 4); }
;             float Pp = 1.f, E = 0.f;
; #pragma unroll
;             for (int v = 0; v < 16; ++v) {
;                 const float xcv = __uint_as_float(xcb[v] << 16);
;                 const float r = __builtin_amdgcn_rcpf(1.0f + __builtin_amdgcn_exp2f(zr[v]));
;                 const float ig = __builtin_amdgcn_rcpf(1.0f + __builtin_amdgcn_exp2f(zi[v]));
;                 const float a = __builtin_amdgcn_exp2f(cl * r);
;                 const float sq = __builtin_amdgcn_sqrtf(fmaf(-a, a, 1.0f));
;                 const float u = sq * ig * xcv;
;                 E = fmaf(a, E, u); Pp *= a; zr[v] = E; zi[v] = Pp; }
.Llruf_wres:
	ds_read_b128 v[120:123], v160
	ds_read_b128 v[124:127], v160 offset:32
	ds_read_b128 v[168:171], v160 offset:64
	ds_read_b128 v[172:175], v160 offset:96
	ds_read_b128 v[176:179], v160 offset:128
	ds_read_b128 v[180:183], v160 offset:160
	ds_read_b128 v[184:187], v160 offset:192
	ds_read_b128 v[188:191], v160 offset:224
	ds_read_b128 v[236:239], v161 offset:8704
	ds_read_b128 v[240:243], v161 offset:8736
	ds_read_b128 v[244:247], v161 offset:8768
	ds_read_b128 v[248:251], v161 offset:8800
	s_waitcnt lgkmcnt(11)
	v_mfma_f32_32x32x16_bf16 v[32:47], v[120:123], v[204:207], v[0:15]
	s_waitcnt lgkmcnt(10)
	v_mfma_f32_32x32x16_bf16 v[32:47], v[124:127], v[208:211], v[32:47]
	s_waitcnt lgkmcnt(9)
	v_mfma_f32_32x32x16_bf16 v[32:47], v[168:171], v[212:215], v[32:47]
	s_waitcnt lgkmcnt(8)
	v_mfma_f32_32x32x16_bf16 v[32:47], v[172:175], v[216:219], v[32:47]
	s_waitcnt lgkmcnt(7)
	v_mfma_f32_32x32x16_bf16 v[32:47], v[176:179], v[220:223], v[32:47]
	s_waitcnt lgkmcnt(6)
	v_mfma_f32_32x32x16_bf16 v[32:47], v[180:183], v[224:227], v[32:47]
	s_waitcnt lgkmcnt(5)
	v_mfma_f32_32x32x16_bf16 v[32:47], v[184:187], v[228:231], v[32:47]
	s_waitcnt lgkmcnt(4)
	v_mfma_f32_32x32x16_bf16 v[32:47], v[188:191], v[232:235], v[32:47]
	s_waitcnt lgkmcnt(3)
	v_mfma_f32_32x32x16_bf16 v[48:63], v[120:123], v[236:239], v[16:31]
	ds_read_b128 v[236:239], v161 offset:8832
	s_nop 8
	v_exp_f32_e32 v32, v32
	v_exp_f32_e32 v33, v33
	v_exp_f32_e32 v34, v34
	v_fma_f32 v32, v32, v138, v138
	v_rcp_f32_e32 v32, v32
	s_waitcnt lgkmcnt(3)
	v_mfma_f32_32x32x16_bf16 v[48:63], v[124:127], v[240:243], v[48:63]
	ds_read_b128 v[240:243], v161 offset:8864
	v_fma_f32 v33, v33, v138, v138
	v_rcp_f32_e32 v33, v33
	s_nop 0
	s_waitcnt lgkmcnt(3)
	v_mfma_f32_32x32x16_bf16 v[48:63], v[168:171], v[244:247], v[48:63]
	ds_read_b128 v[244:247], v161 offset:8896
	v_exp_f32_e32 v33, v33
	s_waitcnt lgkmcnt(3)
	v_mfma_f32_32x32x16_bf16 v[48:63], v[172:175], v[248:251], v[48:63]
	ds_read_b128 v[248:251], v161 offset:8928
	ds_read_u16 v152, v162
	ds_read_u16 v154, v162 offset:272
	ds_read_u16 v155, v162 offset:544
	ds_read_u16 v157, v162 offset:816
	ds_read_u16 v196, v162 offset:1088
	ds_read_u16 v197, v162 offset:1360
	s_waitcnt lgkmcnt(5)
	v_lshlrev_b32_e32 v152, 16, v152
	s_waitcnt lgkmcnt(4)
	v_lshlrev_b32_e32 v154, 16, v154
	v_mfma_f32_32x32x16_bf16 v[48:63], v[176:179], v[236:239], v[48:63]
	ds_read_u16 v177, v162 offset:1632
	ds_read_u16 v178, v162 offset:1904
	ds_read_u16 v127, v163
	ds_read_u16 v124, v163 offset:80
	ds_read_u16 v121, v163 offset:160
	ds_read_u16 v66, v163 offset:240
	ds_read_u16 v64, v163 offset:320
	ds_read_u16 v126, v163 offset:400
	ds_read_u16 v123, v163 offset:480
	ds_read_u16 v120, v163 offset:560
	v_mfma_f32_32x32x16_bf16 v[48:63], v[180:183], v[240:243], v[48:63]
	v_exp_f32_e32 v171, v32
	ds_read_u16 v179, v162 offset:2176
	ds_read_u16 v180, v162 offset:2448
	ds_read_u16 v181, v162 offset:2720
	v_mfma_f32_32x32x16_bf16 v[48:63], v[184:187], v[244:247], v[48:63]
	ds_read_u16 v182, v162 offset:2992
	ds_read_u16 v183, v162 offset:3264
	ds_read_u16 v184, v162 offset:3536
	ds_read_u16 v185, v162 offset:3808
	ds_read_u16 v187, v162 offset:4080
	v_mfma_f32_32x32x16_bf16 v[48:63], v[188:191], v[248:251], v[48:63]
	s_nop 11
	v_exp_f32_e32 v172, v48
	ds_read_u16 v170, v163 offset:640
	ds_read_u16 v169, v163 offset:720
	ds_read_u16 v168, v163 offset:800
	ds_read_u16 v166, v163 offset:880
	ds_read_u16 v125, v163 offset:960
	ds_read_u16 v122, v163 offset:1040
	ds_read_u16 v67, v163 offset:1120
	ds_read_u16 v48, v163 offset:1200
	v_add_f32_e32 v32, 1.0, v172
	v_fma_f32 v172, -v171, v171, 1.0
	v_rcp_f32_e32 v32, v32
	v_sqrt_f32_e32 v172, v172
	s_nop 0
	v_mul_f32_e32 v32, v172, v32
	v_exp_f32_e32 v172, v49
	v_mul_f32_e32 v49, v32, v152
	v_fma_f32 v152, -v33, v33, 1.0
	v_sqrt_f32_e32 v152, v152
	v_add_f32_e32 v32, 1.0, v172
	v_rcp_f32_e32 v32, v32
	v_fmac_f32_e32 v49, 0, v171
	v_mul_f32_e32 v32, v152, v32
	v_mul_f32_e32 v172, v32, v154
	v_fma_f32 v32, v34, v138, v138
	v_rcp_f32_e32 v32, v32
	v_exp_f32_e32 v34, v50
	v_fmac_f32_e32 v172, v33, v49
	v_mul_f32_e32 v50, v171, v33
	v_exp_f32_e32 v32, v32
	v_add_f32_e32 v33, 1.0, v34
	v_exp_f32_e32 v34, v35
	v_rcp_f32_e32 v33, v33
	v_fma_f32 v35, -v32, v32, 1.0
	v_sqrt_f32_e32 v35, v35
	v_fma_f32 v34, v34, v138, v138
	v_rcp_f32_e32 v34, v34
	s_waitcnt lgkmcnt(14)
; template <int dir>
; __device__ __forceinline__ void lru_pass(LAS unsigned char* lds, const Params& P, int b, int h, int q, bool dry) {
;     ...
;             for (int v = 0; v < 16; ++v) {
;                 const float xcv = __uint_as_float(xcb[v] << 16);
;                 const float r = __builtin_amdgcn_rcpf(1.0f + __builtin_amdgcn_exp2f(zr[v]));
;                 const float ig = __builtin_amdgcn_rcpf(1.0f + __builtin_amdgcn_exp2f(zi[v]));
;                 const float a = __builtin_amdgcn_exp2f(cl * r);
;                 const float sq = __builtin_amdgcn_sqrtf(fmaf(-a, a, 1.0f));
;                 const float u = sq * ig * xcv;
;                 E = fmaf(a, E, u); Pp *= a; zr[v] = E; zi[v] = Pp; }
;             const float Po = __shfl_xor(Pp, 32), Eo = __shfl_xor(E, 32);
;             const float P0 = g ? Po : Pp, E0 = g ? Eo : E, P1 = g ? Pp : Po, E1 = g ? E : Eo;
;             if (g == 0) { AGG[(wid * 2 + 0) * 32 + nl] = P0 * P1; AGG[(wid * 2 + 1) * 32 + nl] = fmaf(P1, E0, E1); }
	v_lshlrev_b32_e32 v152, 16, v155
	v_mul_f32_e32 v33, v35, v33
	v_mul_f32_e32 v173, v33, v152
	v_exp_f32_e32 v33, v51
	v_exp_f32_e32 v34, v34
	v_fmac_f32_e32 v173, v32, v172
	v_mul_f32_e32 v51, v32, v50
	v_exp_f32_e32 v32, v36
	v_add_f32_e32 v33, 1.0, v33
	v_fma_f32 v35, -v34, v34, 1.0
	v_rcp_f32_e32 v33, v33
	v_sqrt_f32_e32 v35, v35
	v_fma_f32 v32, v32, v138, v138
	v_rcp_f32_e32 v32, v32
	v_lshlrev_b32_e32 v36, 16, v157
	v_mul_f32_e32 v33, v35, v33
	v_mul_f32_e32 v174, v33, v36
	v_fmac_f32_e32 v174, v34, v173
	v_exp_f32_e32 v33, v52
	v_mul_f32_e32 v52, v34, v51
	v_exp_f32_e32 v32, v32
	v_exp_f32_e32 v34, v37
	v_add_f32_e32 v33, 1.0, v33
	v_rcp_f32_e32 v33, v33
	v_fma_f32 v35, -v32, v32, 1.0
	v_fma_f32 v34, v34, v138, v138
	v_sqrt_f32_e32 v35, v35
	v_rcp_f32_e32 v34, v34
	v_lshlrev_b32_e32 v36, 16, v196
	v_mul_f32_e32 v33, v35, v33
	v_mul_f32_e32 v175, v33, v36
	v_exp_f32_e32 v33, v53
	v_exp_f32_e32 v34, v34
	v_fmac_f32_e32 v175, v32, v174
	v_mul_f32_e32 v53, v32, v52
	v_exp_f32_e32 v32, v38
	v_add_f32_e32 v33, 1.0, v33
	v_fma_f32 v35, -v34, v34, 1.0
	v_rcp_f32_e32 v33, v33
	v_sqrt_f32_e32 v35, v35
	v_fma_f32 v32, v32, v138, v138
	v_rcp_f32_e32 v32, v32
	v_lshlrev_b32_e32 v36, 16, v197
	v_mul_f32_e32 v33, v35, v33
	v_mul_f32_e32 v176, v33, v36
	v_fmac_f32_e32 v176, v34, v175
	v_exp_f32_e32 v33, v54
	v_mul_f32_e32 v54, v34, v53
	v_exp_f32_e32 v32, v32
	v_exp_f32_e32 v34, v39
	v_add_f32_e32 v33, 1.0, v33
	v_rcp_f32_e32 v33, v33
	v_fma_f32 v35, -v32, v32, 1.0
	v_fma_f32 v34, v34, v138, v138
	v_sqrt_f32_e32 v35, v35
	v_rcp_f32_e32 v34, v34
	v_lshlrev_b32_e32 v36, 16, v177
	v_mul_f32_e32 v33, v35, v33
	v_mul_f32_e32 v177, v33, v36
	v_exp_f32_e32 v33, v55
	v_exp_f32_e32 v34, v34
	v_fmac_f32_e32 v177, v32, v176
	v_mul_f32_e32 v55, v32, v54
	v_exp_f32_e32 v32, v40
	v_add_f32_e32 v33, 1.0, v33
	v_fma_f32 v35, -v34, v34, 1.0
	v_rcp_f32_e32 v33, v33
	v_sqrt_f32_e32 v35, v35
	v_fma_f32 v32, v32, v138, v138
	v_rcp_f32_e32 v32, v32
	v_lshlrev_b32_e32 v36, 16, v178
	v_mul_f32_e32 v33, v35, v33
	v_mul_f32_e32 v178, v33, v36
	v_fmac_f32_e32 v178, v34, v177
	v_exp_f32_e32 v33, v56
	v_mul_f32_e32 v56, v34, v55
	v_exp_f32_e32 v32, v32
	v_exp_f32_e32 v34, v41
	v_add_f32_e32 v33, 1.0, v33
	v_rcp_f32_e32 v33, v33
	v_fma_f32 v35, -v32, v32, 1.0
	v_fma_f32 v34, v34, v138, v138
	v_sqrt_f32_e32 v35, v35
	v_rcp_f32_e32 v34, v34
	v_lshlrev_b32_e32 v36, 16, v179
	v_mul_f32_e32 v33, v35, v33
	v_mul_f32_e32 v179, v33, v36
	v_exp_f32_e32 v33, v57
	v_exp_f32_e32 v34, v34
	v_fmac_f32_e32 v179, v32, v178
	v_mul_f32_e32 v57, v32, v56
	v_exp_f32_e32 v32, v42
	v_add_f32_e32 v33, 1.0, v33
	v_fma_f32 v35, -v34, v34, 1.0
	v_rcp_f32_e32 v33, v33
	v_sqrt_f32_e32 v35, v35
	v_fma_f32 v32, v32, v138, v138
	v_rcp_f32_e32 v32, v32
	v_lshlrev_b32_e32 v36, 16, v180
	v_mul_f32_e32 v33, v35, v33
	v_mul_f32_e32 v180, v33, v36
	v_fmac_f32_e32 v180, v34, v179
	v_exp_f32_e32 v33, v58
	v_mul_f32_e32 v58, v34, v57
	v_exp_f32_e32 v32, v32
	v_exp_f32_e32 v34, v43
	v_add_f32_e32 v33, 1.0, v33
	v_rcp_f32_e32 v33, v33
	v_fma_f32 v35, -v32, v32, 1.0
	v_fma_f32 v34, v34, v138, v138
	v_sqrt_f32_e32 v35, v35
	v_rcp_f32_e32 v34, v34
	s_waitcnt lgkmcnt(13)
	v_lshlrev_b32_e32 v36, 16, v181
	v_mul_f32_e32 v33, v35, v33
	v_mul_f32_e32 v181, v33, v36
	v_exp_f32_e32 v33, v59
	v_exp_f32_e32 v34, v34
	v_fmac_f32_e32 v181, v32, v180
	v_mul_f32_e32 v59, v32, v58
	v_exp_f32_e32 v32, v44
	v_add_f32_e32 v33, 1.0, v33
	v_fma_f32 v35, -v34, v34, 1.0
	v_rcp_f32_e32 v33, v33
	v_sqrt_f32_e32 v35, v35
	v_fma_f32 v32, v32, v138, v138
	v_rcp_f32_e32 v32, v32
	s_waitcnt lgkmcnt(12)
	v_lshlrev_b32_e32 v36, 16, v182
	v_mul_f32_e32 v33, v35, v33
	v_mul_f32_e32 v182, v33, v36
	v_fmac_f32_e32 v182, v34, v181
	v_exp_f32_e32 v33, v60
	v_mul_f32_e32 v60, v34, v59
	v_exp_f32_e32 v32, v32
	v_exp_f32_e32 v34, v45
	v_add_f32_e32 v33, 1.0, v33
	v_rcp_f32_e32 v33, v33
	v_fma_f32 v35, -v32, v32, 1.0
	v_fma_f32 v34, v34, v138, v138
	v_sqrt_f32_e32 v35, v35
	v_rcp_f32_e32 v34, v34
	s_waitcnt lgkmcnt(11)
	v_lshlrev_b32_e32 v36, 16, v183
	v_mul_f32_e32 v33, v35, v33
	v_mul_f32_e32 v183, v33, v36
	v_exp_f32_e32 v33, v61
	v_exp_f32_e32 v34, v34
	v_fmac_f32_e32 v183, v32, v182
	v_mul_f32_e32 v61, v32, v60
	v_exp_f32_e32 v32, v46
	v_add_f32_e32 v33, 1.0, v33
	v_fma_f32 v35, -v34, v34, 1.0
	v_rcp_f32_e32 v33, v33
	v_sqrt_f32_e32 v35, v35
	v_fma_f32 v32, v32, v138, v138
	v_rcp_f32_e32 v32, v32
	s_waitcnt lgkmcnt(10)
	v_lshlrev_b32_e32 v36, 16, v184
	v_mul_f32_e32 v33, v35, v33
	v_mul_f32_e32 v184, v33, v36
	v_fmac_f32_e32 v184, v34, v183
	v_exp_f32_e32 v33, v62
	v_mul_f32_e32 v62, v34, v61
	v_exp_f32_e32 v34, v47
	v_exp_f32_e32 v32, v32
	v_add_f32_e32 v33, 1.0, v33
	v_rcp_f32_e32 v33, v33
	v_fma_f32 v34, v34, v138, v138
	v_fma_f32 v35, -v32, v32, 1.0
	v_rcp_f32_e32 v34, v34
	v_sqrt_f32_e32 v35, v35
	s_waitcnt lgkmcnt(9)
	v_lshlrev_b32_e32 v36, 16, v185
	v_mul_f32_e32 v186, v32, v62
	v_mul_f32_e32 v33, v35, v33
	v_exp_f32_e32 v35, v63
	v_exp_f32_e32 v34, v34
	v_mul_f32_e32 v63, v33, v36
	v_fmac_f32_e32 v63, v32, v184
	v_add_f32_e32 v33, 1.0, v35
	v_fma_f32 v35, -v34, v34, 1.0
	v_rcp_f32_e32 v33, v33
	v_sqrt_f32_e32 v35, v35
	s_waitcnt lgkmcnt(8)
	v_lshlrev_b32_e32 v32, 16, v187
	v_mul_f32_e32 v187, v34, v186
	v_mul_f32_e32 v33, v35, v33
	v_mul_f32_e32 v185, v33, v32
	v_fmac_f32_e32 v185, v34, v63
	v_mov_b32_e32 v188, v187
	v_mov_b32_e32 v252, v187
	v_mov_b32_e32 v189, v185
	v_mov_b32_e32 v253, v185
	s_nop 1
	v_permlane32_swap_b32 v188, v252
	v_permlane32_swap_b32 v189, v253
	s_and_saveexec_b64 s[18:19], vcc
	s_cbranch_execz .LBB0_299
	v_fma_f32 v32, v252, v189, v253
	v_mul_f32_e32 v33, v188, v252
	v_add_u32_e32 v35, s98, v147
	ds_write2_b32 v35, v33, v32 offset1:32

; #define LAS __attribute__((address_space(3)))
; #define LDS_BARRIER() do { asm volatile("s_waitcnt lgkmcnt(0)" ::: "memory"); __builtin_amdgcn_s_barrier(); asm volatile("" ::: "memory"); } while (0)
; template <int dir>
; __device__ __forceinline__ void lru_pass(LAS unsigned char* lds, const Params& P, int b, int h, int q, bool dry) {
;     ...
;     {
; #pragma unroll
;         for (int i = 0; i < 2; ++i) { const int idx = tid + i * NTHREADS, gate = idx >> 9, n = (idx >> 4) & 31, kc = idx & 15;
;             *(LAS u32x4*)(WB + (gate * 32 + n) * XC_PITCH + kc * 16) = *(const u32x4*)(LruW + ((size_t)((dir * 2 + gate) * 8 + h) * 128 + q * 32 + n) * 128 + kc * 8); }
;         const float br = -LOG2E * P.lru_ba[(dir * 8 + h) * 128 + chl], bi = -LOG2E * P.lru_bx[(dir * 8 + h) * 128 + chl];
;         const float lam = P.lru_lambda[dir * 1024 + ch];
;         const float cl = -8.0f * LOG2E * log1pf(__expf(-lam));
;         float carry = 0.f;
;         LruTile cur = lru_tile(Z, ZC, b, h, dir, 0);
;         u32x4 rows[11];
;         constexpr int NIN = dir == 0 ? 2 : 4;
;         u32x4 inr[NIN];
;         lru_load_rows(rows, cur, tr, cgp);
;     ...
;         LDS_BARRIER();
;         if (dir == 0) {
; #pragma unroll
;             for (int i = 0; i < 4; ++i) { const int id = tid + i * NTHREADS; *(u32x4*)(Hg + (size_t)(t0_prev + (id >> 3)) * DM + (id & 7) * 4) = *(const LAS u32x4*)(TOUT + (id >> 3) * IO_WP + (id & 7) * 16); }
.Lpp_f_noy:
	s_waitcnt lgkmcnt(0)
	s_barrier
	v_add_u32_e32 v0, v129, v149
	ds_read_b128 v[0:3], v0
	v_add_u32_e32 v4, s97, v148
	v_ashrrev_i32_e32 v5, 31, v4
	v_lshlrev_b64 v[4:5], 12, v[4:5]
	v_lshl_add_u64 v[8:9], v[130:131], 0, v[4:5]
	v_add_u32_e32 v4, v129, v146
	ds_read_b128 v[4:7], v4
	s_waitcnt lgkmcnt(1)
	global_store_dwordx4 v[8:9], v[0:3], off
	v_cmp_gt_i32_e32 vcc, 64, v128
	s_nop 0
	v_add_u32_e32 v0, s97, v145
	v_ashrrev_i32_e32 v1, 31, v0
	v_lshlrev_b64 v[0:1], 12, v[0:1]
	v_lshl_add_u64 v[0:1], v[130:131], 0, v[0:1]
	s_waitcnt lgkmcnt(0)
	global_store_dwordx4 v[0:1], v[4:7], off
	v_add_u32_e32 v0, v129, v144
	ds_read_b128 v[0:3], v0
	v_add_u32_e32 v4, s97, v143
	v_ashrrev_i32_e32 v5, 31, v4
	v_lshlrev_b64 v[4:5], 12, v[4:5]
	v_lshl_add_u64 v[8:9], v[130:131], 0, v[4:5]
	v_add_u32_e32 v4, v129, v142
	ds_read_b128 v[4:7], v4
	s_waitcnt lgkmcnt(1)
	global_store_dwordx4 v[8:9], v[0:3], off
	s_nop 1
	v_add_u32_e32 v0, s97, v141
	v_ashrrev_i32_e32 v1, 31, v0
	v_lshlrev_b64 v[0:1], 12, v[0:1]
	v_lshl_add_u64 v[0:1], v[130:131], 0, v[0:1]
	s_waitcnt lgkmcnt(0)
	global_store_dwordx4 v[0:1], v[4:7], off
	s_waitcnt lgkmcnt(0)
	v_mov_b32_e32 v32, v167
	s_barrier
	s_or_b32 s0, s26, 16
	v_and_b32_e32 v15, 31, v32
	v_or_b32_e32 v17, s28, v15
	v_add_u32_e32 v13, 0x200, v32
	v_or_b32_e32 v8, s27, v17
	v_ashrrev_i32_e32 v11, 9, v32
	v_ashrrev_i32_e32 v14, 9, v13
	v_lshlrev_b32_e32 v8, 2, v8
	v_mov_b32_e32 v9, v65
	v_lshl_add_u32 v2, v11, 3, s0
	v_lshl_add_u32 v6, v14, 3, s0
	v_lshl_add_u64 v[8:9], s[64:65], 0, v[8:9]
	s_movk_i32 s0, 0x1000
	v_add_co_u32_e32 v8, vcc, s0, v8
	v_and_b32_e32 v12, 15, v32
	s_nop 0
	v_addc_co_u32_e32 v9, vcc, 0, v9, vcc
	global_load_dword v16, v[8:9], off
	v_bfe_u32 v10, v32, 4, 5
	v_lshlrev_b32_e32 v64, 4, v12
	v_ashrrev_i32_e32 v3, 31, v2
	v_ashrrev_i32_e32 v7, 31, v6
	v_or_b32_e32 v4, s28, v10
	v_lshl_add_u64 v[0:1], s[38:39], 0, v[64:65]
	v_lshlrev_b64 v[2:3], 15, v[2:3]
	v_lshlrev_b64 v[6:7], 15, v[6:7]
	v_lshlrev_b32_e32 v4, 8, v4
	v_mov_b32_e32 v5, v65
	v_lshl_add_u64 v[2:3], v[0:1], 0, v[2:3]
	v_lshl_add_u64 v[0:1], v[0:1], 0, v[6:7]
	v_lshl_add_u64 v[2:3], v[2:3], 0, v[4:5]
	v_lshl_add_u64 v[4:5], v[0:1], 0, v[4:5]
	global_load_dwordx4 v[0:3], v[2:3], off
	s_nop 0
	global_load_dwordx4 v[4:7], v[4:5], off
	v_lshrrev_b32_e32 v8, 1, v32
	v_lshlrev_b32_e32 v9, 2, v32
	v_and_b32_e32 v20, 12, v8
	v_lshl_or_b32 v11, v11, 5, v10
	v_add_u32_e32 v8, s88, v64
	v_lshl_or_b32 v14, v14, 5, v10
	v_mad_u64_u32 v[10:11], s[6:7], v11, s89, v[8:9]
	s_or_b32 s8, s26, 8
	v_and_or_b32 v20, v9, 16, v20
	v_lshlrev_b32_e32 v21, 2, v17
	v_mad_u64_u32 v[8:9], s[6:7], v14, s89, v[8:9]
	v_lshl_or_b32 v9, s8, 9, v21
	global_load_dword v14, v9, s[58:59]
	s_nop 0
	global_load_dword v9, v9, s[62:63]
	s_mov_b32 s80, 0x3f2aaaab
	s_mov_b32 s81, 0x3f317218
	s_mov_b32 s91, 0x7f800000
	s_mov_b32 s92, 0x33800000
	v_ashrrev_i32_e32 v33, 4, v32
	v_lshlrev_b32_e32 v34, 3, v12
	v_readfirstlane_b32 s4, v32
	s_lshl_b64 s[0:1], s[78:79], 11
	s_lshl_b32 s5, s8, 14
	s_ashr_i32 s6, s4, 6
	s_add_u32 s26, s0, s5
	s_addc_u32 s27, s1, 0
	s_lshl_b32 s0, s28, 1
	v_readlane_b32 s1, v255, 10
	v_and_b32_e32 v19, 3, v32
	s_add_u32 s0, s1, s0
	v_bfe_u32 v18, v32, 5, 1
	v_add_u32_e32 v44, 0, v64
	v_lshlrev_b32_e32 v64, 4, v19
	s_addc_u32 s1, s3, 0
	v_lshl_add_u64 v[136:137], s[0:1], 0, v[64:65]
	s_lshl_b32 s0, s6, 5
	v_lshlrev_b32_e32 v46, 4, v18
	v_or_b32_e32 v37, s0, v46
	v_add_u32_e32 v158, s86, v64
	v_or_b32_e32 v64, 4, v37
	s_movk_i32 s93, 0x880
	v_ashrrev_i32_e32 v36, 3, v32
	v_ashrrev_i32_e32 v38, 3, v13
	v_ashrrev_i32_e32 v140, 2, v32
	v_sub_u32_e32 v39, 0xff, v37
	v_sub_u32_e32 v64, 0xff, v64
	v_lshl_add_u32 v160, v33, 3, -1
	v_mul_lo_u32 v52, v33, s93
	v_lshl_or_b32 v110, v33, 13, v34
	v_mov_b32_e32 v111, v65
	v_lshlrev_b64 v[110:111], 1, v[110:111]
	v_lshl_add_u64 v[108:109], s[48:49], 0, v[110:111]
	global_load_dwordx4 v[68:71], v[108:109], off offset:-2048
	global_load_dwordx4 v[72:75], v[108:109], off
	global_load_dwordx4 v[76:79], v[108:109], off offset:2048
	v_lshl_add_u64 v[108:109], s[50:51], 0, v[110:111]
	global_load_dwordx4 v[80:83], v[108:109], off
	v_lshl_add_u64 v[108:109], s[56:57], 0, v[110:111]
	global_load_dwordx4 v[84:87], v[108:109], off
	v_lshl_add_u64 v[108:109], s[60:61], 0, v[110:111]
	global_load_dwordx4 v[88:91], v[108:109], off
	v_lshl_add_u64 v[108:109], s[66:67], 0, v[110:111]
	global_load_dwordx4 v[92:95], v[108:109], off
	v_lshl_add_u64 v[108:109], s[70:71], 0, v[110:111]
	global_load_dwordx4 v[96:99], v[108:109], off
	v_lshl_add_u64 v[108:109], s[72:73], 0, v[110:111]
	global_load_dwordx4 v[100:103], v[108:109], off
	v_lshl_add_u64 v[108:109], s[74:75], 0, v[110:111]
	global_load_dwordx4 v[104:107], v[108:109], off
	v_lshl_add_u64 v[108:109], s[76:77], 0, v[110:111]
	global_load_dwordx4 v[108:111], v[108:109], off
	s_waitcnt vmcnt(14)
	ds_write_b128 v10, v[0:3]
	s_waitcnt vmcnt(13)
; #define LAS __attribute__((address_space(3)))
; template <int dir>
; __device__ __forceinline__ void lru_pass(LAS unsigned char* lds, const Params& P, int b, int h, int q, bool dry) {
;     ...
;     {
; #pragma unroll
;         for (int i = 0; i < 2; ++i) { const int idx = tid + i * NTHREADS, gate = idx >> 9, n = (idx >> 4) & 31, kc = idx & 15;
;             *(LAS u32x4*)(WB + (gate * 32 + n) * XC_PITCH + kc * 16) = *(const u32x4*)(LruW + ((size_t)((dir * 2 + gate) * 8 + h) * 128 + q * 32 + n) * 128 + kc * 8); }
;         const float br = -LOG2E * P.lru_ba[(dir * 8 + h) * 128 + chl], bi = -LOG2E * P.lru_bx[(dir * 8 + h) * 128 + chl];
;         const float lam = P.lru_lambda[dir * 1024 + ch];
;         const float cl = -8.0f * LOG2E * log1pf(__expf(-lam));
;         float carry = 0.f;
;         LruTile cur = lru_tile(Z, ZC, b, h, dir, 0);
;         u32x4 rows[11];
;         constexpr int NIN = dir == 0 ? 2 : 4;
;         u32x4 inr[NIN];
;         lru_load_rows(rows, cur, tr, cgp);
	ds_write_b128 v8, v[4:7]
	v_mul_f32_e32 v11, 0xbfb8aa3b, v16
	v_exp_f32_e32 v11, v11
	v_mul_lo_u32 v57, v39, s89
	v_mul_lo_u32 v58, v39, s30
	v_mul_lo_u32 v114, v64, s89
	v_add_f32_e32 v2, 1.0, v11
	v_add_f32_e32 v3, -1.0, v2
	v_frexp_mant_f32_e32 v4, v2
	v_cvt_f64_f32_e32 v[0:1], v2
	v_sub_f32_e32 v5, v3, v2
	v_frexp_exp_i32_f64_e32 v0, v[0:1]
	v_cmp_gt_f32_e32 vcc, s80, v4
	v_sub_f32_e32 v3, v11, v3
	v_add_f32_e32 v1, 1.0, v5
	v_subbrev_co_u32_e32 v0, vcc, 0, v0, vcc
	v_add_f32_e32 v1, v3, v1
	v_sub_u32_e32 v3, 0, v0
	v_ldexp_f32 v2, v2, v3
	v_ldexp_f32 v1, v1, v3
	v_add_f32_e32 v3, -1.0, v2
	v_add_f32_e32 v4, 1.0, v2
	v_add_f32_e32 v5, 1.0, v3
	v_add_f32_e32 v6, -1.0, v4
	v_sub_f32_e32 v5, v2, v5
	v_sub_f32_e32 v2, v2, v6
	v_add_f32_e32 v5, v1, v5
	v_add_f32_e32 v1, v1, v2
	v_add_f32_e32 v7, v4, v1
	v_rcp_f32_e32 v8, v7
	v_add_f32_e32 v2, v3, v5
	v_sub_f32_e32 v4, v7, v4
	v_sub_f32_e32 v3, v2, v3
	v_sub_f32_e32 v1, v1, v4
	v_mul_f32_e32 v4, v2, v8
	v_sub_f32_e32 v3, v5, v3
	v_mul_f32_e32 v5, v7, v4
	v_fma_f32 v10, v4, v7, -v5
	v_fmac_f32_e32 v10, v4, v1
	v_add_f32_e32 v16, v5, v10
	v_sub_f32_e32 v21, v2, v16
	v_sub_f32_e32 v2, v2, v21
	v_sub_f32_e32 v5, v16, v5
	v_sub_f32_e32 v2, v2, v16
	v_sub_f32_e32 v5, v5, v10
	v_add_f32_e32 v2, v3, v2
	v_add_f32_e32 v2, v5, v2
	v_add_f32_e32 v3, v21, v2
	v_mul_f32_e32 v5, v8, v3
	v_sub_f32_e32 v10, v21, v3
	v_mul_f32_e32 v16, v7, v5
	v_add_f32_e32 v2, v2, v10
	v_add_f32_e32 v10, v4, v5
	v_fma_f32 v7, v5, v7, -v16
	v_sub_f32_e32 v4, v10, v4
	v_fmac_f32_e32 v7, v5, v1
	v_sub_f32_e32 v1, v5, v4
	v_add_f32_e32 v4, v16, v7
	v_sub_f32_e32 v5, v4, v16
	v_sub_f32_e32 v16, v3, v4
	v_sub_f32_e32 v3, v3, v16
	v_sub_f32_e32 v3, v3, v4
	v_cvt_f32_i32_e32 v0, v0
	v_sub_f32_e32 v5, v5, v7
	v_add_f32_e32 v2, v2, v3
	v_add_f32_e32 v2, v5, v2
	v_add_f32_e32 v2, v16, v2
	v_mul_f32_e32 v2, v8, v2
	v_mul_f32_e32 v6, 0x3f317218, v0
	v_add_f32_e32 v1, v1, v2
	v_add_f32_e32 v2, v10, v1
	v_fma_f32 v5, v0, s81, -v6
	v_fmac_f32_e32 v5, 0xb102e308, v0
	v_sub_f32_e32 v0, v2, v10
	v_mul_f32_e32 v3, v2, v2
	v_sub_f32_e32 v0, v1, v0
	v_add_f32_e32 v1, v6, v5
	v_fmamk_f32 v4, v3, 0x3e9b6dac, v200
	v_sub_f32_e32 v6, v1, v6
	v_fmaak_f32 v4, v3, v4, 0x3f2aaada
	v_sub_f32_e32 v5, v5, v6
	v_ldexp_f32 v6, v2, 1
	v_mul_f32_e32 v2, v2, v3
	v_mul_f32_e32 v2, v2, v4
	v_add_f32_e32 v3, v6, v2
	v_sub_f32_e32 v4, v3, v6
	v_ldexp_f32 v0, v0, 1
	v_sub_f32_e32 v2, v2, v4
	v_add_f32_e32 v0, v0, v2
	v_add_f32_e32 v2, v3, v0
	v_sub_f32_e32 v3, v2, v3
	v_sub_f32_e32 v0, v0, v3
	v_add_f32_e32 v3, v1, v2
	v_sub_f32_e32 v4, v3, v1
	v_sub_f32_e32 v6, v3, v4
	v_sub_f32_e32 v1, v1, v6
	v_sub_f32_e32 v2, v2, v4
	v_add_f32_e32 v1, v2, v1
	v_add_f32_e32 v2, v5, v0
	v_sub_f32_e32 v4, v2, v5
	v_add_f32_e32 v1, v2, v1
	v_sub_f32_e32 v6, v2, v4
	v_add_f32_e32 v2, v3, v1
	v_sub_f32_e32 v5, v5, v6
	v_sub_f32_e32 v0, v0, v4
	v_sub_f32_e32 v3, v2, v3
	v_add_f32_e32 v0, v0, v5
	v_sub_f32_e32 v1, v1, v3
	v_add_f32_e32 v0, v0, v1
	v_add_f32_e32 v0, v2, v0
	v_cmp_neq_f32_e32 vcc, s91, v11
	v_mov_b32_e32 v1, v65
	v_mul_lo_u32 v115, v64, s30
	v_cndmask_b32_e32 v0, v201, v0, vcc
	v_cmp_ngt_f32_e32 vcc, -1.0, v11
	v_mul_lo_u32 v206, v39, s87
	v_mul_lo_u32 v210, v64, s87
	v_cndmask_b32_e32 v0, v202, v0, vcc
	v_cmp_neq_f32_e32 vcc, -1.0, v11
	v_ashrrev_i32_e32 v39, 31, v38
	v_sub_u32_e32 v41, 0xfe, v37
	v_cndmask_b32_e32 v0, v203, v0, vcc
	v_cmp_lt_f32_e64 vcc, |v11|, s92
	v_mul_lo_u32 v59, v41, s89
	v_mul_lo_u32 v60, v41, s30
	v_cndmask_b32_e32 v6, v0, v11, vcc
	v_lshlrev_b32_e32 v2, 4, v32
	v_and_b32_e32 v2, 0x70, v2
	v_lshlrev_b32_e32 v1, 2, v15
	v_add_u32_e32 v45, s95, v2
	v_or3_b32 v2, v19, v20, s0
	s_and_b32 s0, s4, 0x3fffffc0
	v_add_u32_e32 v161, s94, v1
	s_cmp_eq_u32 s6, 7
	v_lshl_add_u32 v254, s0, 2, v161
	s_cselect_b64 s[0:1], -1, 0
	s_cmp_eq_u32 s6, 6
	s_cselect_b64 s[16:17], -1, 0
	s_cmp_eq_u32 s6, 5
	s_cselect_b64 s[4:5], -1, 0
	s_cmp_eq_u32 s6, 4
	s_cselect_b64 s[8:9], -1, 0
	s_cmp_eq_u32 s6, 3
	s_cselect_b64 s[10:11], -1, 0
	s_cmp_eq_u32 s6, 2
	s_cselect_b64 s[12:13], -1, 0
	s_cmp_eq_u32 s6, 1
	s_cselect_b64 s[14:15], -1, 0
	s_lshl_b32 s6, s25, 7
	s_and_b32 s6, s6, 0xe00
	s_lshl_b32 s7, s29, 7
	s_or_b32 s6, s7, s6
	s_add_u32 s6, s6, s44
	v_add_u32_e32 v50, s95, v1
	v_add_u32_e32 v1, 0x400, v32
	s_addc_u32 s7, 0, s45
	v_ashrrev_i32_e32 v40, 3, v1
	v_add_u32_e32 v1, 0x600, v32
	v_and_b32_e32 v32, 7, v32
	s_add_u32 s18, s84, s46
	v_lshlrev_b32_e32 v64, 4, v32
	v_lshl_or_b32 v32, v33, 10, v34
	v_mov_b32_e32 v33, v65
	s_addc_u32 s19, s85, s47
	v_lshl_add_u64 v[144:145], v[32:33], 1, s[18:19]
	v_lshlrev_b64 v[32:33], 12, v[38:39]
	v_lshl_add_u64 v[32:33], s[6:7], 0, v[32:33]
	v_mul_lo_u32 v207, v41, s87
	v_lshl_add_u64 v[32:33], v[32:33], 0, v[64:65]
	v_ashrrev_i32_e32 v41, 31, v40
	v_or_b32_e32 v43, 2, v37
	v_lshl_add_u64 v[252:253], s[42:43], 0, v[32:33]
	v_lshlrev_b64 v[32:33], 12, v[40:41]
	v_ashrrev_i32_e32 v42, 3, v1
	v_sub_u32_e32 v43, 0xff, v43
	v_or_b32_e32 v63, 3, v37
	v_or_b32_e32 v66, 5, v37
	v_or_b32_e32 v67, 6, v37
	v_or_b32_e32 v120, 7, v37
	v_or_b32_e32 v123, 8, v37
	v_or_b32_e32 v126, 9, v37
	v_or_b32_e32 v129, 10, v37
	v_or_b32_e32 v132, 11, v37
	v_or_b32_e32 v135, 12, v37
	v_or_b32_e32 v142, 13, v37
	v_or_b32_e32 v143, 14, v37
	v_or_b32_e32 v37, 15, v37
	v_lshl_add_u64 v[32:33], s[6:7], 0, v[32:33]
	v_mul_lo_u32 v61, v43, s89
	v_mul_lo_u32 v62, v43, s30
	v_sub_u32_e32 v37, 0xff, v37
	v_mul_lo_u32 v208, v43, s87
	v_lshl_add_u64 v[32:33], v[32:33], 0, v[64:65]
	v_ashrrev_i32_e32 v43, 31, v42
	v_sub_u32_e32 v2, 0xff, v2
	v_mul_lo_u32 v204, v37, s89
	v_mul_lo_u32 v205, v37, s30
	v_mul_lo_u32 v221, v37, s87
	v_ashrrev_i32_e32 v37, 31, v36
	v_lshl_add_u64 v[154:155], s[42:43], 0, v[32:33]
	v_lshlrev_b64 v[32:33], 12, v[42:43]
	v_mul_lo_u32 v2, v2, s89
	v_mul_lo_u32 v53, v36, s30
	v_sub_u32_e32 v63, 0xff, v63
	v_sub_u32_e32 v66, 0xff, v66
	v_sub_u32_e32 v67, 0xff, v67
	v_sub_u32_e32 v120, 0xff, v120
	v_sub_u32_e32 v123, 0xff, v123
	v_sub_u32_e32 v126, 0xff, v126
	v_lshlrev_b64 v[36:37], 12, v[36:37]
	v_lshl_add_u64 v[32:33], s[6:7], 0, v[32:33]
	v_lshlrev_b32_e32 v35, 5, v12
	v_add_u32_e32 v47, 0, v2
	v_mov_b32_e32 v2, s88
	v_lshl_add_u32 v49, v17, 1, 0
	v_lshl_add_u32 v51, v15, 1, s86
	v_mul_lo_u32 v112, v63, s89
	v_mul_lo_u32 v113, v63, s30
	v_mul_lo_u32 v116, v66, s89
	v_mul_lo_u32 v117, v66, s30
	v_mul_lo_u32 v118, v67, s89
	v_mul_lo_u32 v119, v67, s30
	v_mul_lo_u32 v121, v120, s89
	v_mul_lo_u32 v122, v120, s30
	v_mul_lo_u32 v124, v123, s89
	v_mul_lo_u32 v125, v123, s30
	v_mul_lo_u32 v127, v126, s89
	v_mul_lo_u32 v128, v126, s30
	v_sub_u32_e32 v129, 0xff, v129
	v_sub_u32_e32 v132, 0xff, v132
	v_sub_u32_e32 v135, 0xff, v135
	v_sub_u32_e32 v142, 0xff, v142
	v_sub_u32_e32 v143, 0xff, v143
	v_mul_lo_u32 v211, v66, s87
	v_mul_lo_u32 v212, v67, s87
	v_mul_lo_u32 v120, v120, s87
	v_mul_lo_u32 v123, v123, s87
	v_mul_lo_u32 v126, v126, s87
	v_lshl_add_u64 v[36:37], s[6:7], 0, v[36:37]
	v_lshl_add_u64 v[32:33], v[32:33], 0, v[64:65]
	v_mov_b32_e32 v66, v65
	v_mov_b32_e32 v67, v65
	s_waitcnt vmcnt(12)
; template <int dir>
; __device__ __forceinline__ void lru_pass(LAS unsigned char* lds, const Params& P, int b, int h, int q, bool dry) {
;     ...
;         const float br = -LOG2E * P.lru_ba[(dir * 8 + h) * 128 + chl], bi = -LOG2E * P.lru_bx[(dir * 8 + h) * 128 + chl];
;         const float lam = P.lru_lambda[dir * 1024 + ch];
;         const float cl = -8.0f * LOG2E * log1pf(__expf(-lam));
;         float carry = 0.f;
;         LruTile cur = lru_tile(Z, ZC, b, h, dir, 0);
;         u32x4 rows[11];
;         constexpr int NIN = dir == 0 ? 2 : 4;
;         u32x4 inr[NIN];
;         lru_load_rows(rows, cur, tr, cgp);
; #pragma unroll
;         for (int i = 0; i < NIN; ++i) inr[i] = (u32x4){0u, 0u, 0u, 0u};
;         int t0_prev = 0;
;     ...
;             f32x16 zr, zi;
; #pragma unroll
;             for (int v = 0; v < 16; ++v) { zr[v] = br; zi[v] = bi; }
;             const int sbase = 32 * wid + 16 * g;
	v_mul_f32_e32 v0, 0xbfb8aa3b, v14
	s_waitcnt vmcnt(11)
	v_mul_f32_e32 v16, 0xbfb8aa3b, v9
	v_mad_u32_u24 v48, v15, s89, v2
	v_mul_lo_u32 v54, v38, s30
	v_mul_lo_u32 v55, v40, s30
	v_mul_lo_u32 v56, v42, s30
	v_ashrrev_i32_e32 v138, 2, v13
	v_mul_lo_u32 v130, v129, s89
	v_mul_lo_u32 v131, v129, s30
	v_mul_lo_u32 v133, v132, s89
	v_mul_lo_u32 v134, v132, s30
	v_mul_lo_u32 v146, v135, s89
	v_mul_lo_u32 v147, v135, s30
	v_mul_lo_u32 v148, v142, s89
	v_mul_lo_u32 v149, v142, s30
	v_mul_lo_u32 v162, v143, s89
	v_mul_lo_u32 v163, v143, s30
	v_mul_lo_u32 v63, v63, s87
	v_mul_lo_u32 v129, v129, s87
	v_mul_lo_u32 v132, v132, s87
	v_mul_lo_u32 v135, v135, s87
	v_mul_lo_u32 v219, v142, s87
	v_mul_lo_u32 v220, v143, s87
	v_lshl_add_u64 v[36:37], v[36:37], 0, v[64:65]
	v_lshl_add_u64 v[150:151], s[42:43], 0, v[32:33]
	v_mov_b32_e32 v64, v65
	v_add_u32_e32 v32, 0, v35
	v_add_u32_e32 v180, v49, v112
	v_add_u32_e32 v181, v50, v113
	v_add_u32_e32 v182, v49, v114
	v_add_u32_e32 v183, v50, v115
	v_add_u32_e32 v184, v49, v116
	v_add_u32_e32 v185, v50, v117
	v_add_u32_e32 v186, v49, v118
	v_add_u32_e32 v187, v50, v119
	v_add_u32_e32 v188, v49, v121
	v_add_u32_e32 v189, v50, v122
	v_add_u32_e32 v190, v49, v124
	v_add_u32_e32 v191, v50, v125
	v_add_u32_e32 v192, v49, v127
	v_add_u32_e32 v213, v51, v120
	v_add_u32_e32 v214, v51, v123
	v_add_u32_e32 v215, v51, v126
	v_mov_b64_e32 v[114:115], v[66:67]
	v_mov_b64_e32 v[118:119], v[66:67]
	v_mov_b64_e32 v[122:123], v[66:67]
	v_mov_b64_e32 v[126:127], v[66:67]
	s_mov_b32 s78, 0
	v_mov_b32_e32 v156, 0xff800000
	v_mul_f32_e32 v159, 0xc138aa3b, v6
	v_rcp_f32_e32 v159, v159
	s_nop 0
	v_cmp_eq_u32_e32 vcc, 0, v18
	v_mul_lo_u32 v164, v140, s87
	v_ashrrev_i32_e32 v141, 31, v140
	v_mul_lo_u32 v152, v138, s87
	v_ashrrev_i32_e32 v139, 31, v138
	v_mov_b32_e32 v1, v0
	v_mov_b32_e32 v2, v0
	v_mov_b32_e32 v3, v0
	v_mov_b32_e32 v4, v0
	v_mov_b32_e32 v5, v0
	v_mov_b32_e32 v6, v0
	v_mov_b32_e32 v7, v0
	v_mov_b32_e32 v8, v0
	v_mov_b32_e32 v9, v0
	v_mov_b32_e32 v10, v0
	v_mov_b32_e32 v11, v0
	v_mov_b32_e32 v12, v0
	v_mov_b32_e32 v13, v0
	v_mov_b32_e32 v14, v0
	v_mov_b32_e32 v15, v0
	v_mov_b32_e32 v17, v16
	v_mov_b32_e32 v18, v16
	v_mov_b32_e32 v19, v16
	v_mov_b32_e32 v20, v16
	v_mov_b32_e32 v21, v16
	v_mov_b32_e32 v22, v16
	v_mov_b32_e32 v23, v16
	v_mov_b32_e32 v24, v16
	v_mov_b32_e32 v25, v16
	v_mov_b32_e32 v26, v16
	v_mov_b32_e32 v27, v16
	v_mov_b32_e32 v28, v16
	v_mov_b32_e32 v29, v16
	v_mov_b32_e32 v30, v16
	v_mov_b32_e32 v31, v16
	v_lshl_add_u64 v[142:143], s[42:43], 0, v[36:37]
	s_movk_i32 s28, 0x100
	v_mov_b32_e32 v222, 0
	s_mov_b64 s[44:45], 0
	s_movk_i32 s25, 0x700
	v_add_u32_e32 v165, 0x15c00, v32
	v_add_u32_e32 v166, v44, v52
	v_add_u32_e32 v168, v45, v53
	v_add_u32_e32 v169, v45, v54
	v_add_u32_e32 v170, v45, v55
	v_add_u32_e32 v171, v45, v56
	v_add_u32_e32 v172, v47, v46
	v_add_u32_e32 v173, v48, v46
	v_add_u32_e32 v174, v49, v57
	v_add_u32_e32 v175, v50, v58
	v_add_u32_e32 v176, v49, v59
	v_add_u32_e32 v177, v50, v60
	v_add_u32_e32 v178, v49, v61
	v_add_u32_e32 v179, v50, v62
	v_add_u32_e32 v193, v50, v128
	v_add_u32_e32 v194, v49, v130
	v_add_u32_e32 v195, v50, v131
	v_add_u32_e32 v196, v49, v133
	v_add_u32_e32 v197, v50, v134
	v_add_u32_e32 v198, v49, v146
	v_add_u32_e32 v199, v50, v147
	v_add_u32_e32 v200, v49, v148
	v_add_u32_e32 v201, v50, v149
	v_add_u32_e32 v202, v49, v162
	v_add_u32_e32 v203, v50, v163
	v_add_u32_e32 v204, v49, v204
	v_add_u32_e32 v205, v50, v205
	v_add_u32_e32 v206, v51, v206
	v_add_u32_e32 v207, v51, v207
	v_add_u32_e32 v208, v51, v208
	v_add_u32_e32 v209, v51, v63
	v_add_u32_e32 v210, v51, v210
	v_add_u32_e32 v211, v51, v211
	v_add_u32_e32 v212, v51, v212
	v_add_u32_e32 v216, v51, v129
	v_add_u32_e32 v217, v51, v132
	v_add_u32_e32 v218, v51, v135
	v_add_u32_e32 v219, v51, v219
	v_add_u32_e32 v220, v51, v220
	v_add_u32_e32 v221, v51, v221
; #define LAS __attribute__((address_space(3)))
; template <int dir>
; __device__ __forceinline__ void lru_pass(LAS unsigned char* lds, const Params& P, int b, int h, int q, bool dry) {
;     ...
;         int t0_prev = 0;
;         for (int sc = 0; sc < 9; ++sc) {
;             const bool isctx = (sc == 0);
;             const int t0 = cur.t0;
; #pragma unroll
;             for (int j = 0; j < 11; ++j) { if (j != 0 && j < 9) continue;
;                 const int t = t0 + tr * 8 - 1 + j; if (t < 0 || t >= cur.L) rows[j] = (u32x4){0u, 0u, 0u, 0u}; }
;     ...
;             const int sbase = 32 * wid + 16 * g;
;             { const int sl = 32 * wid + s_i; const int tlA = dir == 0 ? sl : 255 - sl;
;               const LAS unsigned char* ap = XC + tlA * XC_PITCH + 16 * g;
;               const LAS unsigned char* wrp = WB + nl * XC_PITCH + 16 * g; const LAS unsigned char* wip = wrp + 32 * XC_PITCH;
	v_mov_b64_e32 v[112:113], v[64:65]
	v_mov_b64_e32 v[116:117], v[64:65]
	v_mov_b64_e32 v[120:121], v[64:65]
	v_mov_b64_e32 v[124:125], v[64:65]
	s_mov_b32 s46, 0
	s_mov_b32 s29, 0
	v_lshrrev_b32_e32 v32, 8, v167
	v_mul_u32_u24_e32 v33, 0x3600, v32
	v_add_u32_e32 v168, v168, v33
	v_add_u32_e32 v169, v169, v33
	v_add_u32_e32 v170, v170, v33
	v_add_u32_e32 v171, v171, v33
	v_add_u32_e32 v169, 0xffffee00, v169
	v_add_u32_e32 v170, 0xffffdc00, v170
	v_add_u32_e32 v171, 0xffffca00, v171
	v_mul_u32_u24_e32 v66, 0x60000, v32
	v_mov_b32_e32 v67, 0
	v_lshl_add_u64 v[142:143], v[66:67], 0, v[142:143]
	v_lshl_add_u64 v[252:253], v[66:67], 0, v[252:253]
	v_lshl_add_u64 v[154:155], v[66:67], 0, v[154:155]
	v_lshl_add_u64 v[150:151], v[66:67], 0, v[150:151]
	s_mov_b32 s19, -1
	s_mov_b32 s18, 0xfffe0000
	v_lshl_add_u64 v[252:253], v[252:253], 0, s[18:19]
	s_mov_b32 s18, 0xfffc0000
	v_lshl_add_u64 v[154:155], v[154:155], 0, s[18:19]
	s_mov_b32 s18, 0xfffa0000
	v_lshl_add_u64 v[150:151], v[150:151], 0, s[18:19]
	v_mul_u32_u24_e32 v33, 0x1400, v32
	v_add_u32_e32 v164, v164, v33
	v_add_u32_e32 v152, v152, v33
	v_add_u32_e32 v152, 0xffffec00, v152
	v_lshlrev_b32_e32 v33, 6, v32
	v_add_u32_e32 v140, v140, v33
	v_add_u32_e32 v138, v138, v33
	v_add_u32_e32 v138, 0xffffffc0, v138
	v_lshrrev_b32_e32 v33, 6, v167
	s_nop 1
	v_readfirstlane_b32 s18, v33
	s_lshl_b32 s19, s18, 6
	s_sub_i32 s19, s19, 0xe0
	s_mul_i32 s20, s19, 0x110
	v_add_u32_e32 v172, s20, v172
	v_add_u32_e32 v174, s20, v174
	v_add_u32_e32 v176, s20, v176
	v_add_u32_e32 v178, s20, v178
	v_add_u32_e32 v180, s20, v180
	v_add_u32_e32 v182, s20, v182
	v_add_u32_e32 v184, s20, v184
	v_add_u32_e32 v186, s20, v186
	v_add_u32_e32 v188, s20, v188
	v_add_u32_e32 v190, s20, v190
	v_add_u32_e32 v192, s20, v192
	v_add_u32_e32 v194, s20, v194
	v_add_u32_e32 v196, s20, v196
	v_add_u32_e32 v198, s20, v198
	v_add_u32_e32 v200, s20, v200
	v_add_u32_e32 v202, s20, v202
	v_add_u32_e32 v204, s20, v204
	s_mul_i32 s20, s19, 0x90
	v_add_u32_e32 v175, s20, v175
	v_add_u32_e32 v177, s20, v177
	v_add_u32_e32 v179, s20, v179
	v_add_u32_e32 v181, s20, v181
	v_add_u32_e32 v183, s20, v183
	v_add_u32_e32 v185, s20, v185
	v_add_u32_e32 v187, s20, v187
	v_add_u32_e32 v189, s20, v189
	v_add_u32_e32 v191, s20, v191
	v_add_u32_e32 v193, s20, v193
	v_add_u32_e32 v195, s20, v195
	v_add_u32_e32 v197, s20, v197
	v_add_u32_e32 v199, s20, v199
	v_add_u32_e32 v201, s20, v201
	v_add_u32_e32 v203, s20, v203
	v_add_u32_e32 v205, s20, v205
	s_mul_i32 s20, s19, 0x50
	v_add_u32_e32 v206, s20, v206
	v_add_u32_e32 v207, s20, v207
	v_add_u32_e32 v208, s20, v208
	v_add_u32_e32 v209, s20, v209
	v_add_u32_e32 v210, s20, v210
	v_add_u32_e32 v211, s20, v211
	v_add_u32_e32 v212, s20, v212
	v_add_u32_e32 v213, s20, v213
	v_add_u32_e32 v214, s20, v214
	v_add_u32_e32 v215, s20, v215
	v_add_u32_e32 v216, s20, v216
	v_add_u32_e32 v217, s20, v217
	v_add_u32_e32 v218, s20, v218
	v_add_u32_e32 v219, s20, v219
	v_add_u32_e32 v220, s20, v220
	v_add_u32_e32 v221, s20, v221
	s_lshl_b32 s20, s18, 1
	s_sub_i32 s20, 7, s20
	s_lshl_b32 s20, s20, 8
	v_add_u32_e32 v254, s20, v254
	s_sub_i32 s18, 7, s18
	s_lshr_b32 s101, s18, 2
	s_or_b32 s19, s18, 4
	s_cmp_eq_u32 s19, 7
	s_cselect_b64 s[0:1], -1, 0
	s_cmp_eq_u32 s19, 6
	s_cselect_b64 s[16:17], -1, 0
	s_cmp_eq_u32 s19, 5
	s_cselect_b64 s[4:5], -1, 0
	s_cmp_eq_u32 s19, 4
	s_cselect_b64 s[8:9], -1, 0
	s_cmp_eq_u32 s19, 3
	s_cselect_b64 s[10:11], -1, 0
	s_cmp_eq_u32 s19, 2
	s_cselect_b64 s[12:13], -1, 0
	s_cmp_eq_u32 s19, 1
	s_cselect_b64 s[14:15], -1, 0
	s_mov_b32 s98, 0
	s_cmp_eq_u32 s101, 0
	s_cselect_b32 s99, 0x14400, 0
	s_cselect_b32 s100, 0, 0x400
	v_add_u32_e32 v33, 0x14000, v254
	v_mov_b32_e32 v66, 1.0
	v_mov_b32_e32 v67, 0
	ds_write2_b32 v33, v66, v67 offset1:32
	s_cmp_eq_u32 s101, 0
	s_cbranch_scc1 .Lpp_b_nox
	s_waitcnt lgkmcnt(0)
	s_barrier

; #define LAS __attribute__((address_space(3)))
; template <int dir>
; __device__ __forceinline__ void lru_pass(LAS unsigned char* lds, const Params& P, int b, int h, int q, bool dry) {
;     ...
;             { const int sl = 32 * wid + s_i; const int tlA = dir == 0 ? sl : 255 - sl;
;               const LAS unsigned char* ap = XC + tlA * XC_PITCH + 16 * g;
;               const LAS unsigned char* wrp = WB + nl * XC_PITCH + 16 * g; const LAS unsigned char* wip = wrp + 32 * XC_PITCH;
; #pragma unroll
;               for (int ks = 0; ks < 8; ++ks) { const bf16x8 A = *(const LAS bf16x8*)(ap + 32 * ks);
;                   const bf16x8 Br = *(const LAS bf16x8*)(wrp + 32 * ks), Bi = *(const LAS bf16x8*)(wip + 32 * ks);
;                   zr = __builtin_amdgcn_mfma_f32_32x32x16_bf16(A, Br, zr, 0, 0, 0); zi = __builtin_amdgcn_mfma_f32_32x32x16_bf16(A, Bi, zi, 0, 0, 0); } }
;             unsigned xcb[16], pk[16];
; #pragma unroll
;             for (int v = 0; v < 16; ++v) { const int s = sbase + v; const int tl = dir == 0 ? s : 255 - s; xcb[v] = *(const LAS bf16_t*)(XC + tl * XC_PITCH + chl * 2);
;                 if (dir == 0) pk[v] = *(const LAS bf16_t*)(TIN + tl * IO_NP + nl * 2); else pk[v] = *(const LAS unsigned*)(TIN + tl * IO_WP + nl * 4); }
;             float Pp = 1.f, E = 0.f;
; #pragma unroll
;             for (int v = 0; v < 16; ++v) {
;                 const float xcv = __uint_as_float(xcb[v] << 16);
;                 const float r = __builtin_amdgcn_rcpf(1.0f + __builtin_amdgcn_exp2f(zr[v]));
;                 const float ig = __builtin_amdgcn_rcpf(1.0f + __builtin_amdgcn_exp2f(zi[v]));
;                 const float a = __builtin_amdgcn_exp2f(cl * r);
;                 const float sq = __builtin_amdgcn_sqrtf(fmaf(-a, a, 1.0f));
;                 const float u = sq * ig * xcv;
;                 E = fmaf(a, E, u); Pp *= a; zr[v] = E; zi[v] = Pp; }
.LBB0_311:
	ds_read_b128 v[128:131], v172
	ds_read_b128 v[48:51], v173
	ds_read_b128 v[132:135], v172 offset:32
	ds_read_b128 v[52:55], v173 offset:32
	s_waitcnt lgkmcnt(2)
	v_mfma_f32_32x32x16_bf16 v[32:47], v[128:131], v[48:51], v[0:15]
	s_waitcnt lgkmcnt(0)
	v_mfma_f32_32x32x16_bf16 v[32:47], v[132:135], v[52:55], v[32:47]
	ds_read_b128 v[224:227], v172 offset:64
	ds_read_b128 v[48:51], v173 offset:64
	ds_read_b128 v[228:231], v172 offset:96
	ds_read_b128 v[52:55], v173 offset:96
	s_waitcnt lgkmcnt(2)
	v_mfma_f32_32x32x16_bf16 v[32:47], v[224:227], v[48:51], v[32:47]
	s_waitcnt lgkmcnt(0)
	v_mfma_f32_32x32x16_bf16 v[32:47], v[228:231], v[52:55], v[32:47]
	ds_read_b128 v[232:235], v172 offset:128
	ds_read_b128 v[48:51], v173 offset:128
	ds_read_b128 v[236:239], v172 offset:160
	ds_read_b128 v[52:55], v173 offset:160
	s_waitcnt lgkmcnt(2)
	v_mfma_f32_32x32x16_bf16 v[32:47], v[232:235], v[48:51], v[32:47]
	s_waitcnt lgkmcnt(0)
	v_mfma_f32_32x32x16_bf16 v[32:47], v[236:239], v[52:55], v[32:47]
	ds_read_b128 v[240:243], v172 offset:192
	ds_read_b128 v[48:51], v173 offset:192
	ds_read_b128 v[244:247], v172 offset:224
	ds_read_b128 v[52:55], v173 offset:224
	ds_read_b128 v[248:251], v173 offset:8704
	ds_read_b128 v[146:149], v173 offset:8736
	s_waitcnt lgkmcnt(4)
	v_mfma_f32_32x32x16_bf16 v[32:47], v[240:243], v[48:51], v[32:47]
	s_waitcnt lgkmcnt(2)
	v_mfma_f32_32x32x16_bf16 v[32:47], v[244:247], v[52:55], v[32:47]
	s_waitcnt lgkmcnt(1)
	v_mfma_f32_32x32x16_bf16 v[48:63], v[128:131], v[248:251], v[16:31]
	s_nop 9
	v_exp_f32_e32 v32, v32
	v_exp_f32_e32 v33, v33
	v_exp_f32_e32 v34, v34
	v_fma_f32 v32, v32, v159, v159
	v_rcp_f32_e32 v32, v32
	v_fma_f32 v33, v33, v159, v159
	s_waitcnt lgkmcnt(0)
	v_mfma_f32_32x32x16_bf16 v[48:63], v[132:135], v[146:149], v[48:63]
	ds_read_b128 v[128:131], v173 offset:8768
	ds_read_b128 v[132:135], v173 offset:8800
	v_rcp_f32_e32 v33, v33
	s_nop 0
	s_waitcnt lgkmcnt(1)
	v_mfma_f32_32x32x16_bf16 v[48:63], v[224:227], v[128:131], v[48:63]
	v_exp_f32_e32 v227, v32
	v_exp_f32_e32 v33, v33
	s_waitcnt lgkmcnt(0)
	v_mfma_f32_32x32x16_bf16 v[48:63], v[228:231], v[132:135], v[48:63]
	ds_read_b128 v[128:131], v173 offset:8832
	ds_read_b128 v[132:135], v173 offset:8864
	ds_read_b128 v[146:149], v173 offset:8896
	ds_read_b128 v[228:231], v173 offset:8928
	s_waitcnt lgkmcnt(3)
	v_mfma_f32_32x32x16_bf16 v[48:63], v[232:235], v[128:131], v[48:63]
	ds_read_u16 v162, v174
	ds_read_b32 v226, v175
	ds_read_u16 v163, v176
	ds_read_b32 v225, v177
	ds_read_u16 v232, v178
	ds_read_b32 v224, v179
	ds_read_u16 v233, v180
	ds_read_b32 v223, v181
	s_waitcnt lgkmcnt(7)
	v_lshlrev_b32_e32 v162, 16, v162
	s_waitcnt lgkmcnt(5)
	v_lshlrev_b32_e32 v163, 16, v163
	v_mfma_f32_32x32x16_bf16 v[48:63], v[236:239], v[132:135], v[48:63]
	ds_read_u16 v234, v182
	ds_read_b32 v135, v183
	ds_read_u16 v235, v184
	ds_read_b32 v134, v185
	ds_read_u16 v236, v186
	ds_read_b32 v133, v187
	ds_read_u16 v237, v188
	ds_read_b32 v131, v189
	v_mfma_f32_32x32x16_bf16 v[48:63], v[240:243], v[146:149], v[48:63]
	ds_read_u16 v146, v190
	ds_read_b32 v132, v191
	ds_read_u16 v147, v192
	ds_read_b32 v130, v193
	ds_read_u16 v148, v194
	ds_read_b32 v129, v195
	ds_read_u16 v149, v196
	ds_read_b32 v128, v197
	v_mfma_f32_32x32x16_bf16 v[48:63], v[244:247], v[228:231], v[48:63]
	s_nop 11
	v_exp_f32_e32 v228, v48
	ds_read_u16 v239, v198
	ds_read_b32 v67, v199
	ds_read_u16 v240, v200
	ds_read_b32 v66, v201
	ds_read_u16 v241, v202
	ds_read_b32 v64, v203
	ds_read_u16 v242, v204
	ds_read_b32 v48, v205
	v_add_f32_e32 v32, 1.0, v228
	v_fma_f32 v228, -v227, v227, 1.0
	v_rcp_f32_e32 v32, v32
	v_sqrt_f32_e32 v228, v228
	s_nop 0
	v_mul_f32_e32 v32, v228, v32
	v_exp_f32_e32 v228, v49
	v_mul_f32_e32 v49, v32, v162
	v_fma_f32 v162, -v33, v33, 1.0
	v_sqrt_f32_e32 v162, v162
	v_add_f32_e32 v32, 1.0, v228
	v_rcp_f32_e32 v32, v32
	v_fmac_f32_e32 v49, 0, v227
	v_mul_f32_e32 v32, v162, v32
	v_mul_f32_e32 v228, v32, v163
	v_fma_f32 v32, v34, v159, v159
	v_rcp_f32_e32 v32, v32
	v_exp_f32_e32 v34, v50
	v_fmac_f32_e32 v228, v33, v49
	v_mul_f32_e32 v50, v227, v33
	v_exp_f32_e32 v32, v32
	v_add_f32_e32 v33, 1.0, v34
	v_exp_f32_e32 v34, v35
	v_rcp_f32_e32 v33, v33
	v_fma_f32 v35, -v32, v32, 1.0
	v_sqrt_f32_e32 v35, v35
	v_fma_f32 v34, v34, v159, v159
	v_rcp_f32_e32 v34, v34
	s_waitcnt lgkmcnt(14)
; template <int dir>
; __device__ __forceinline__ void lru_pass(LAS unsigned char* lds, const Params& P, int b, int h, int q, bool dry) {
;     ...
;             for (int v = 0; v < 16; ++v) {
;                 const float xcv = __uint_as_float(xcb[v] << 16);
;                 const float r = __builtin_amdgcn_rcpf(1.0f + __builtin_amdgcn_exp2f(zr[v]));
;                 const float ig = __builtin_amdgcn_rcpf(1.0f + __builtin_amdgcn_exp2f(zi[v]));
;                 const float a = __builtin_amdgcn_exp2f(cl * r);
;                 const float sq = __builtin_amdgcn_sqrtf(fmaf(-a, a, 1.0f));
;                 const float u = sq * ig * xcv;
;                 E = fmaf(a, E, u); Pp *= a; zr[v] = E; zi[v] = Pp; }
;             const float Po = __shfl_xor(Pp, 32), Eo = __shfl_xor(E, 32);
;             const float P0 = g ? Po : Pp, E0 = g ? Eo : E, P1 = g ? Pp : Po, E1 = g ? E : Eo;
;             if (g == 0) { AGG[(wid * 2 + 0) * 32 + nl] = P0 * P1; AGG[(wid * 2 + 1) * 32 + nl] = fmaf(P1, E0, E1); }
	v_lshlrev_b32_e32 v162, 16, v232
	v_mul_f32_e32 v33, v35, v33
	v_mul_f32_e32 v229, v33, v162
	v_exp_f32_e32 v33, v51
	v_exp_f32_e32 v34, v34
	v_fmac_f32_e32 v229, v32, v228
	v_mul_f32_e32 v51, v32, v50
	v_exp_f32_e32 v32, v36
	v_add_f32_e32 v33, 1.0, v33
	v_fma_f32 v35, -v34, v34, 1.0
	v_rcp_f32_e32 v33, v33
	v_sqrt_f32_e32 v35, v35
	v_fma_f32 v32, v32, v159, v159
	v_rcp_f32_e32 v32, v32
	v_lshlrev_b32_e32 v36, 16, v233
	v_mul_f32_e32 v33, v35, v33
	v_mul_f32_e32 v230, v33, v36
	v_fmac_f32_e32 v230, v34, v229
	v_exp_f32_e32 v33, v52
	v_mul_f32_e32 v52, v34, v51
	v_exp_f32_e32 v32, v32
	v_exp_f32_e32 v34, v37
	v_add_f32_e32 v33, 1.0, v33
	v_rcp_f32_e32 v33, v33
	v_fma_f32 v35, -v32, v32, 1.0
	v_fma_f32 v34, v34, v159, v159
	v_sqrt_f32_e32 v35, v35
	v_rcp_f32_e32 v34, v34
	v_lshlrev_b32_e32 v36, 16, v234
	v_mul_f32_e32 v33, v35, v33
	v_mul_f32_e32 v231, v33, v36
	v_exp_f32_e32 v33, v53
	v_exp_f32_e32 v34, v34
	v_fmac_f32_e32 v231, v32, v230
	v_mul_f32_e32 v53, v32, v52
	v_exp_f32_e32 v32, v38
	v_add_f32_e32 v33, 1.0, v33
	v_fma_f32 v35, -v34, v34, 1.0
	v_rcp_f32_e32 v33, v33
	v_sqrt_f32_e32 v35, v35
	v_fma_f32 v32, v32, v159, v159
	v_rcp_f32_e32 v32, v32
	v_lshlrev_b32_e32 v36, 16, v235
	v_mul_f32_e32 v33, v35, v33
	v_mul_f32_e32 v232, v33, v36
	v_fmac_f32_e32 v232, v34, v231
	v_exp_f32_e32 v33, v54
	v_mul_f32_e32 v54, v34, v53
	v_exp_f32_e32 v32, v32
	v_exp_f32_e32 v34, v39
	v_add_f32_e32 v33, 1.0, v33
	v_rcp_f32_e32 v33, v33
	v_fma_f32 v35, -v32, v32, 1.0
	v_fma_f32 v34, v34, v159, v159
	v_sqrt_f32_e32 v35, v35
	v_rcp_f32_e32 v34, v34
	v_lshlrev_b32_e32 v36, 16, v236
	v_mul_f32_e32 v33, v35, v33
	v_mul_f32_e32 v233, v33, v36
	v_exp_f32_e32 v33, v55
	v_exp_f32_e32 v34, v34
	v_fmac_f32_e32 v233, v32, v232
	v_mul_f32_e32 v55, v32, v54
	v_exp_f32_e32 v32, v40
	v_add_f32_e32 v33, 1.0, v33
	v_fma_f32 v35, -v34, v34, 1.0
	v_rcp_f32_e32 v33, v33
	v_sqrt_f32_e32 v35, v35
	v_fma_f32 v32, v32, v159, v159
	v_rcp_f32_e32 v32, v32
	v_lshlrev_b32_e32 v36, 16, v237
	v_mul_f32_e32 v33, v35, v33
	v_mul_f32_e32 v234, v33, v36
	v_fmac_f32_e32 v234, v34, v233
	v_exp_f32_e32 v33, v56
	v_mul_f32_e32 v56, v34, v55
	v_exp_f32_e32 v32, v32
	v_exp_f32_e32 v34, v41
	v_add_f32_e32 v33, 1.0, v33
	v_rcp_f32_e32 v33, v33
	v_fma_f32 v35, -v32, v32, 1.0
	v_fma_f32 v34, v34, v159, v159
	v_sqrt_f32_e32 v35, v35
	v_rcp_f32_e32 v34, v34
	v_lshlrev_b32_e32 v36, 16, v146
	v_mul_f32_e32 v33, v35, v33
	v_mul_f32_e32 v235, v33, v36
	v_exp_f32_e32 v33, v57
	v_exp_f32_e32 v34, v34
	v_fmac_f32_e32 v235, v32, v234
	v_mul_f32_e32 v57, v32, v56
	v_exp_f32_e32 v32, v42
	v_add_f32_e32 v33, 1.0, v33
	v_fma_f32 v35, -v34, v34, 1.0
	v_rcp_f32_e32 v33, v33
	v_sqrt_f32_e32 v35, v35
	v_fma_f32 v32, v32, v159, v159
	v_rcp_f32_e32 v32, v32
	s_waitcnt lgkmcnt(13)
	v_lshlrev_b32_e32 v36, 16, v147
	v_mul_f32_e32 v33, v35, v33
	v_mul_f32_e32 v236, v33, v36
	v_fmac_f32_e32 v236, v34, v235
	v_exp_f32_e32 v33, v58
	v_mul_f32_e32 v58, v34, v57
	v_exp_f32_e32 v32, v32
	v_exp_f32_e32 v34, v43
	v_add_f32_e32 v33, 1.0, v33
	v_rcp_f32_e32 v33, v33
	v_fma_f32 v35, -v32, v32, 1.0
	v_fma_f32 v34, v34, v159, v159
	v_sqrt_f32_e32 v35, v35
	v_rcp_f32_e32 v34, v34
	s_waitcnt lgkmcnt(11)
	v_lshlrev_b32_e32 v36, 16, v148
	v_mul_f32_e32 v33, v35, v33
	v_mul_f32_e32 v237, v33, v36
	v_exp_f32_e32 v33, v59
	v_exp_f32_e32 v34, v34
	v_fmac_f32_e32 v237, v32, v236
	v_mul_f32_e32 v59, v32, v58
	v_exp_f32_e32 v32, v44
	v_add_f32_e32 v33, 1.0, v33
	v_fma_f32 v35, -v34, v34, 1.0
	v_rcp_f32_e32 v33, v33
	v_sqrt_f32_e32 v35, v35
	v_fma_f32 v32, v32, v159, v159
	v_rcp_f32_e32 v32, v32
	s_waitcnt lgkmcnt(9)
	v_lshlrev_b32_e32 v36, 16, v149
	v_mul_f32_e32 v33, v35, v33
	v_mul_f32_e32 v238, v33, v36
	v_fmac_f32_e32 v238, v34, v237
	v_exp_f32_e32 v33, v60
	v_mul_f32_e32 v60, v34, v59
	v_exp_f32_e32 v32, v32
	v_exp_f32_e32 v34, v45
	v_add_f32_e32 v33, 1.0, v33
	v_rcp_f32_e32 v33, v33
	v_fma_f32 v35, -v32, v32, 1.0
	v_fma_f32 v34, v34, v159, v159
	v_sqrt_f32_e32 v35, v35
	v_rcp_f32_e32 v34, v34
	s_waitcnt lgkmcnt(7)
	v_lshlrev_b32_e32 v36, 16, v239
	v_mul_f32_e32 v33, v35, v33
	v_mul_f32_e32 v239, v33, v36
	v_exp_f32_e32 v33, v61
	v_exp_f32_e32 v34, v34
	v_fmac_f32_e32 v239, v32, v238
	v_mul_f32_e32 v61, v32, v60
	v_exp_f32_e32 v32, v46
	v_add_f32_e32 v33, 1.0, v33
	v_fma_f32 v35, -v34, v34, 1.0
	v_rcp_f32_e32 v33, v33
	v_sqrt_f32_e32 v35, v35
	v_fma_f32 v32, v32, v159, v159
	v_rcp_f32_e32 v32, v32
	s_waitcnt lgkmcnt(5)
	v_lshlrev_b32_e32 v36, 16, v240
	v_mul_f32_e32 v33, v35, v33
	v_mul_f32_e32 v240, v33, v36
	v_fmac_f32_e32 v240, v34, v239
	v_exp_f32_e32 v33, v62
	v_mul_f32_e32 v62, v34, v61
	v_exp_f32_e32 v34, v47
	v_exp_f32_e32 v32, v32
	v_add_f32_e32 v33, 1.0, v33
	v_rcp_f32_e32 v33, v33
	v_fma_f32 v34, v34, v159, v159
	v_fma_f32 v35, -v32, v32, 1.0
	v_rcp_f32_e32 v34, v34
	v_sqrt_f32_e32 v35, v35
	s_waitcnt lgkmcnt(3)
	v_lshlrev_b32_e32 v36, 16, v241
	v_mul_f32_e32 v243, v32, v62
	v_mul_f32_e32 v33, v35, v33
	v_exp_f32_e32 v35, v63
	v_exp_f32_e32 v34, v34
	v_mul_f32_e32 v63, v33, v36
	v_fmac_f32_e32 v63, v32, v240
	v_add_f32_e32 v33, 1.0, v35
	v_fma_f32 v35, -v34, v34, 1.0
	v_rcp_f32_e32 v33, v33
	v_sqrt_f32_e32 v35, v35
	s_waitcnt lgkmcnt(1)
	v_lshlrev_b32_e32 v32, 16, v242
	v_mul_f32_e32 v242, v34, v243
	v_mul_f32_e32 v33, v35, v33
	v_mul_f32_e32 v241, v33, v32
	v_fmac_f32_e32 v241, v34, v63
	v_mov_b32_e32 v244, v242
	v_mov_b32_e32 v246, v242
	v_mov_b32_e32 v245, v241
	v_mov_b32_e32 v247, v241
	s_nop 1
	v_permlane32_swap_b32 v244, v246
	v_permlane32_swap_b32 v245, v247
	s_and_saveexec_b64 s[18:19], vcc
	s_cbranch_execz .LBB0_313
	v_fma_f32 v32, v246, v245, v247
	v_mul_f32_e32 v33, v244, v246
	v_add_u32_e32 v35, s98, v254
	ds_write2_b32 v35, v33, v32 offset1:32
